# GEMM K-loops: s_setprio 0 moved after the post-MMA barrier (one fewer issue slot on the handover path)
# baseline (speedup 1.0000x reference)
; #define PG8_STAGE(bufoff, gbase, voff) do { _Pragma("unroll") for (int _i = 0; _i < 2; ++_i) \
;         __builtin_amdgcn_global_load_lds((const unsigned*)((const char*)(gbase) + (voff)[_i]), (PG8_LAS unsigned*)(lds + (bufoff) + ldsw + _i * 8192), 16, 0, 0); } while (0)
; #define PG8_LDA(dst, b, h) do { _Pragma("unroll") for (int m = 0; m < 4; ++m) _Pragma("unroll") for (int k = 0; k < 2; ++k) dst[m][k] = *(const PG8_LAS bf16x8*)(lds + PG8_SA(b, h) + aoff + m * 2048 + k * 1024); } while (0)
; #define PG8_LDB(dst, b, h) do { _Pragma("unroll") for (int n = 0; n < 2; ++n) _Pragma("unroll") for (int k = 0; k < 2; ++k) dst[n][k] = *(const PG8_LAS bf16x8*)(lds + PG8_SB(b, h) + boff + n * 2048 + k * 1024); } while (0)
; #define PG8_MMA(ai, bj, At, Bt) do { __builtin_amdgcn_s_setprio(1); _Pragma("unroll") for (int m = 0; m < 4; ++m) _Pragma("unroll") for (int n = 0; n < 2; ++n) _Pragma("unroll") for (int k = 0; k < 2; ++k) \
;         acc[ai][bj][m][n] = __builtin_amdgcn_mfma_f32_16x16x32_bf16(Bt[n][k], At[m][k], acc[ai][bj][m][n], 0, 0, 0); __builtin_amdgcn_s_setprio(0); } while (0)
; #define PG8_WAIT_V(n) asm volatile("s_waitcnt vmcnt(" #n ")" ::: "memory")
; #define PG8_WAIT_L(n) asm volatile("s_waitcnt lgkmcnt(" #n ")" ::: "memory")
; template <class Epi, class Sched, bool ALIGN_EPI = false, bool SP2 = false>
; __device__ __forceinline__ void gemm_phase(PG8_LAS unsigned char* lds, const Gemm g, const Sched& S, const Epi& E, int tid_in) {
;     ...
;             const bool last = (t == nt - 2);
;             const char* a1 = cA + (size_t)(t + 1) * kstep;
;             const char* a2 = last ? nA : cA + (size_t)(t + 2) * kstep; const char* b2 = last ? nB : cB + (size_t)(t + 2) * kstep;
;             const char* a3 = a2 + kstep; const char* b3 = b2 + kstep;
;             if (last && has_next) S.a_ready(nxt);
;             if constexpr (SP2) {
;             PG8_LDB(B0, 0, 0); PG8_LDB(B1, 0, 1); PG8_SCHED; PG8_LDA(At, 0, 0); PG8_STAGE(PG8_SA(1, 1), a1 + hstep, voffA);
;             PG8_WAIT_V(8); PG8_WAIT_L(0); PG8_BAR; PG8_MMA(0, 0, At, B0); PG8_MMA(0, 1, At, B1); PG8_BAR; PG8_SCHED;
;             PG8_LDA(At, 0, 1); PG8_STAGE(PG8_SB(0, 0), b2, voffB); PG8_STAGE(PG8_SB(0, 1), b2 + hstep, voffB); PG8_STAGE(PG8_SA(0, 0), a2, voffA);
;             PG8_WAIT_V(8); PG8_WAIT_L(0); PG8_BAR; PG8_MMA(1, 0, At, B0); PG8_MMA(1, 1, At, B1); PG8_BAR; PG8_SCHED;
.LBB0_59:
	s_add_u32 s28, s6, 0xfff80080
	s_addc_u32 s29, s7, -1
	s_add_i32 s60, 0, 0x10000
	s_cmp_eq_u32 s59, 28
	s_cselect_b32 s31, s23, s29
	s_cselect_b32 s30, s45, s28
	v_add_u32_e32 v32, s60, v149
	s_cselect_b32 s29, s21, s47
	s_cselect_b32 s28, s57, s58
	s_add_i32 s62, 0, 0x14000
	ds_read_b128 v[142:145], v32
	ds_read_b128 v[152:155], v32 offset:1024
	ds_read_b128 v[156:159], v32 offset:2048
	ds_read_b128 v[160:163], v32 offset:3072
	v_add_u32_e32 v32, s62, v149
	ds_read_b128 v[164:167], v32
	ds_read_b128 v[186:189], v32 offset:1024
	ds_read_b128 v[190:193], v32 offset:2048
	ds_read_b128 v[194:197], v32 offset:3072
	v_lshl_add_u64 v[146:147], s[6:7], 0, v[138:139]
	s_add_i32 m0, s42, 0xc000
	ds_read_b128 v[212:215], v151
	ds_read_b128 v[220:223], v151 offset:1024
	ds_read_b128 v[224:227], v151 offset:2048
	ds_read_b128 v[228:231], v151 offset:3072
	ds_read_b128 v[232:235], v151 offset:4096
	ds_read_b128 v[236:239], v151 offset:5120
	ds_read_b128 v[240:243], v151 offset:6144
	ds_read_b128 v[244:247], v151 offset:7168
	global_load_lds_dwordx4 v[146:147], off
	v_lshl_add_u64 v[146:147], s[6:7], 0, v[140:141]
	s_add_i32 m0, s42, 0xe000
	s_nop 0
	global_load_lds_dwordx4 v[146:147], off
	s_waitcnt vmcnt(8)
	s_waitcnt lgkmcnt(0)
	s_setprio 1
	s_barrier
	v_mfma_f32_16x16x32_bf16 v[126:129], v[142:145], v[212:215], v[126:129]
	v_mfma_f32_16x16x32_bf16 v[122:125], v[156:159], v[212:215], v[122:125]
	v_mfma_f32_16x16x32_bf16 v[110:113], v[142:145], v[224:227], v[110:113]
	v_mfma_f32_16x16x32_bf16 v[106:109], v[156:159], v[224:227], v[106:109]
	v_mfma_f32_16x16x32_bf16 v[94:97], v[142:145], v[232:235], v[94:97]
	v_mfma_f32_16x16x32_bf16 v[90:93], v[156:159], v[232:235], v[90:93]
	v_mfma_f32_16x16x32_bf16 v[78:81], v[142:145], v[240:243], v[78:81]
	v_mfma_f32_16x16x32_bf16 v[74:77], v[156:159], v[240:243], v[74:77]
	v_mfma_f32_16x16x32_bf16 v[126:129], v[152:155], v[220:223], v[126:129]
	v_mfma_f32_16x16x32_bf16 v[122:125], v[160:163], v[220:223], v[122:125]
	v_mfma_f32_16x16x32_bf16 v[110:113], v[152:155], v[228:231], v[110:113]
	v_mfma_f32_16x16x32_bf16 v[106:109], v[160:163], v[228:231], v[106:109]
	v_mfma_f32_16x16x32_bf16 v[94:97], v[152:155], v[236:239], v[94:97]
	v_mfma_f32_16x16x32_bf16 v[90:93], v[160:163], v[236:239], v[90:93]
	v_mfma_f32_16x16x32_bf16 v[78:81], v[152:155], v[244:247], v[78:81]
	v_mfma_f32_16x16x32_bf16 v[74:77], v[160:163], v[244:247], v[74:77]
	s_setprio 0
	s_setprio 1
	v_mfma_f32_16x16x32_bf16 v[118:121], v[164:167], v[212:215], v[118:121]
	v_mfma_f32_16x16x32_bf16 v[114:117], v[190:193], v[212:215], v[114:117]
	v_mfma_f32_16x16x32_bf16 v[102:105], v[164:167], v[224:227], v[102:105]
	v_mfma_f32_16x16x32_bf16 v[98:101], v[190:193], v[224:227], v[98:101]
	v_mfma_f32_16x16x32_bf16 v[86:89], v[164:167], v[232:235], v[86:89]
	v_mfma_f32_16x16x32_bf16 v[82:85], v[190:193], v[232:235], v[82:85]
	v_mfma_f32_16x16x32_bf16 v[70:73], v[164:167], v[240:243], v[70:73]
	v_mfma_f32_16x16x32_bf16 v[66:69], v[190:193], v[240:243], v[66:69]
	v_mfma_f32_16x16x32_bf16 v[118:121], v[186:189], v[220:223], v[118:121]
	v_mfma_f32_16x16x32_bf16 v[114:117], v[194:197], v[220:223], v[114:117]
	v_mfma_f32_16x16x32_bf16 v[102:105], v[186:189], v[228:231], v[102:105]
	v_mfma_f32_16x16x32_bf16 v[98:101], v[194:197], v[228:231], v[98:101]
	v_mfma_f32_16x16x32_bf16 v[86:89], v[186:189], v[236:239], v[86:89]
	v_mfma_f32_16x16x32_bf16 v[82:85], v[194:197], v[236:239], v[82:85]
	v_mfma_f32_16x16x32_bf16 v[70:73], v[186:189], v[244:247], v[70:73]
	v_mfma_f32_16x16x32_bf16 v[66:69], v[194:197], v[244:247], v[66:69]
	s_barrier
	s_setprio 0
	s_add_i32 s60, s60, s39
	v_lshl_add_u64 v[146:147], s[28:29], 0, v[134:135]
	s_mov_b32 m0, s60
	ds_read_b128 v[212:215], v151 offset:16384
	ds_read_b128 v[220:223], v151 offset:17408
	ds_read_b128 v[224:227], v151 offset:18432
	ds_read_b128 v[228:231], v151 offset:19456
	ds_read_b128 v[232:235], v151 offset:20480
	ds_read_b128 v[236:239], v151 offset:21504
	ds_read_b128 v[240:243], v151 offset:22528
	ds_read_b128 v[244:247], v151 offset:23552
	global_load_lds_dwordx4 v[146:147], off
	s_add_i32 m0, s60, 0x2000
	s_add_u32 s60, s28, 0x80000
	v_lshl_add_u64 v[168:169], s[28:29], 0, v[130:131]
	s_addc_u32 s61, s29, 0
	s_add_i32 s62, s62, s39
	global_load_lds_dwordx4 v[168:169], off
	v_lshl_add_u64 v[216:217], s[60:61], 0, v[134:135]
	s_mov_b32 m0, s62
	v_lshl_add_u64 v[248:249], s[30:31], 0, v[132:133]
	global_load_lds_dwordx4 v[216:217], off
	v_lshl_add_u64 v[216:217], s[60:61], 0, v[130:131]
	s_add_i32 m0, s62, 0x2000
	s_nop 0
	global_load_lds_dwordx4 v[216:217], off
	v_lshl_add_u64 v[216:217], s[30:31], 0, v[136:137]
	s_mov_b32 m0, s42
	s_nop 0
	global_load_lds_dwordx4 v[216:217], off
	s_mov_b32 m0, s43
	s_nop 0
	global_load_lds_dwordx4 v[248:249], off
	s_waitcnt vmcnt(8)
	s_waitcnt lgkmcnt(0)
	s_setprio 1
	s_barrier
; #define PG8_STAGE(bufoff, gbase, voff) do { _Pragma("unroll") for (int _i = 0; _i < 2; ++_i) \
;         __builtin_amdgcn_global_load_lds((const unsigned*)((const char*)(gbase) + (voff)[_i]), (PG8_LAS unsigned*)(lds + (bufoff) + ldsw + _i * 8192), 16, 0, 0); } while (0)
; #define PG8_LDA(dst, b, h) do { _Pragma("unroll") for (int m = 0; m < 4; ++m) _Pragma("unroll") for (int k = 0; k < 2; ++k) dst[m][k] = *(const PG8_LAS bf16x8*)(lds + PG8_SA(b, h) + aoff + m * 2048 + k * 1024); } while (0)
; #define PG8_LDB(dst, b, h) do { _Pragma("unroll") for (int n = 0; n < 2; ++n) _Pragma("unroll") for (int k = 0; k < 2; ++k) dst[n][k] = *(const PG8_LAS bf16x8*)(lds + PG8_SB(b, h) + boff + n * 2048 + k * 1024); } while (0)
; #define PG8_MMA(ai, bj, At, Bt) do { __builtin_amdgcn_s_setprio(1); _Pragma("unroll") for (int m = 0; m < 4; ++m) _Pragma("unroll") for (int n = 0; n < 2; ++n) _Pragma("unroll") for (int k = 0; k < 2; ++k) \
;         acc[ai][bj][m][n] = __builtin_amdgcn_mfma_f32_16x16x32_bf16(Bt[n][k], At[m][k], acc[ai][bj][m][n], 0, 0, 0); __builtin_amdgcn_s_setprio(0); } while (0)
; #define PG8_WAIT_V(n) asm volatile("s_waitcnt vmcnt(" #n ")" ::: "memory")
; #define PG8_WAIT_L(n) asm volatile("s_waitcnt lgkmcnt(" #n ")" ::: "memory")
; #define PG8_BAR __builtin_amdgcn_s_barrier()
; #define PG8_SCHED __builtin_amdgcn_sched_barrier(0)
; template <class Epi, class Sched, bool ALIGN_EPI = false, bool SP2 = false>
; __device__ __forceinline__ void gemm_phase(PG8_LAS unsigned char* lds, const Gemm g, const Sched& S, const Epi& E, int tid_in) {
;     ...
;             PG8_WAIT_V(8); PG8_WAIT_L(0); PG8_BAR; PG8_MMA(1, 0, At, B0); PG8_MMA(1, 1, At, B1); PG8_BAR; PG8_SCHED;
;             PG8_LDB(B0, 1, 0); PG8_LDB(B1, 1, 1); PG8_SCHED; PG8_LDA(At, 1, 0); PG8_STAGE(PG8_SA(0, 1), a2 + hstep, voffA);
;             PG8_WAIT_V(8); PG8_WAIT_L(0); PG8_BAR; PG8_MMA(0, 0, At, B0); PG8_MMA(0, 1, At, B1); PG8_BAR; PG8_SCHED;
	v_mfma_f32_16x16x32_bf16 v[62:65], v[142:145], v[212:215], v[62:65]
	v_mfma_f32_16x16x32_bf16 v[58:61], v[156:159], v[212:215], v[58:61]
	v_mfma_f32_16x16x32_bf16 v[46:49], v[142:145], v[224:227], v[46:49]
	v_mfma_f32_16x16x32_bf16 v[42:45], v[156:159], v[224:227], v[42:45]
	v_mfma_f32_16x16x32_bf16 v[28:31], v[142:145], v[232:235], v[28:31]
	v_mfma_f32_16x16x32_bf16 v[24:27], v[156:159], v[232:235], v[24:27]
	v_mfma_f32_16x16x32_bf16 v[12:15], v[142:145], v[240:243], v[12:15]
	v_mfma_f32_16x16x32_bf16 v[8:11], v[156:159], v[240:243], v[8:11]
	v_mfma_f32_16x16x32_bf16 v[62:65], v[152:155], v[220:223], v[62:65]
	v_mfma_f32_16x16x32_bf16 v[58:61], v[160:163], v[220:223], v[58:61]
	v_mfma_f32_16x16x32_bf16 v[46:49], v[152:155], v[228:231], v[46:49]
	v_mfma_f32_16x16x32_bf16 v[42:45], v[160:163], v[228:231], v[42:45]
	v_mfma_f32_16x16x32_bf16 v[28:31], v[152:155], v[236:239], v[28:31]
	v_mfma_f32_16x16x32_bf16 v[24:27], v[160:163], v[236:239], v[24:27]
	v_mfma_f32_16x16x32_bf16 v[12:15], v[152:155], v[244:247], v[12:15]
	v_mfma_f32_16x16x32_bf16 v[8:11], v[160:163], v[244:247], v[8:11]
	s_setprio 0
	s_setprio 1
	v_mfma_f32_16x16x32_bf16 v[54:57], v[164:167], v[212:215], v[54:57]
	v_mfma_f32_16x16x32_bf16 v[50:53], v[190:193], v[212:215], v[50:53]
	v_mfma_f32_16x16x32_bf16 v[38:41], v[164:167], v[224:227], v[38:41]
	v_mfma_f32_16x16x32_bf16 v[34:37], v[190:193], v[224:227], v[34:37]
	v_mfma_f32_16x16x32_bf16 v[20:23], v[164:167], v[232:235], v[20:23]
	v_mfma_f32_16x16x32_bf16 v[16:19], v[190:193], v[232:235], v[16:19]
	v_mfma_f32_16x16x32_bf16 v[4:7], v[164:167], v[240:243], v[4:7]
	v_mfma_f32_16x16x32_bf16 v[0:3], v[190:193], v[240:243], v[0:3]
	v_mfma_f32_16x16x32_bf16 v[54:57], v[186:189], v[220:223], v[54:57]
	v_mfma_f32_16x16x32_bf16 v[50:53], v[194:197], v[220:223], v[50:53]
	v_mfma_f32_16x16x32_bf16 v[38:41], v[186:189], v[228:231], v[38:41]
	v_mfma_f32_16x16x32_bf16 v[34:37], v[194:197], v[228:231], v[34:37]
	v_mfma_f32_16x16x32_bf16 v[20:23], v[186:189], v[236:239], v[20:23]
	v_mfma_f32_16x16x32_bf16 v[16:19], v[194:197], v[236:239], v[16:19]
	v_mfma_f32_16x16x32_bf16 v[4:7], v[186:189], v[244:247], v[4:7]
	v_mfma_f32_16x16x32_bf16 v[0:3], v[194:197], v[244:247], v[0:3]
	s_barrier
	s_setprio 0
	s_add_i32 s60, 0, 0x18000
	v_add_u32_e32 v32, s60, v149
	s_add_i32 s61, 0, 0x1c000
	ds_read_b128 v[142:145], v32
	ds_read_b128 v[152:155], v32 offset:1024
	ds_read_b128 v[156:159], v32 offset:2048
	ds_read_b128 v[160:163], v32 offset:3072
	v_add_u32_e32 v32, s61, v149
	ds_read_b128 v[164:167], v32
	ds_read_b128 v[186:189], v32 offset:1024
	ds_read_b128 v[190:193], v32 offset:2048
	ds_read_b128 v[194:197], v32 offset:3072
	s_add_u32 s30, s30, 0x80000
	s_addc_u32 s31, s31, 0
	s_mov_b32 m0, s48
	v_lshl_add_u64 v[250:251], s[30:31], 0, v[136:137]
	ds_read_b128 v[212:215], v151 offset:32768
	ds_read_b128 v[220:223], v151 offset:33792
	ds_read_b128 v[224:227], v151 offset:34816
	ds_read_b128 v[228:231], v151 offset:35840
	ds_read_b128 v[232:235], v151 offset:36864
	ds_read_b128 v[236:239], v151 offset:37888
	ds_read_b128 v[240:243], v151 offset:38912
	ds_read_b128 v[244:247], v151 offset:39936
	global_load_lds_dwordx4 v[250:251], off
	v_lshl_add_u64 v[250:251], s[30:31], 0, v[132:133]
	s_mov_b32 m0, s49
	s_nop 0
	global_load_lds_dwordx4 v[250:251], off
	s_waitcnt vmcnt(8)
	s_waitcnt lgkmcnt(0)
	s_setprio 1
	s_barrier
	v_mfma_f32_16x16x32_bf16 v[126:129], v[142:145], v[212:215], v[126:129]
	v_mfma_f32_16x16x32_bf16 v[122:125], v[156:159], v[212:215], v[122:125]
	v_mfma_f32_16x16x32_bf16 v[110:113], v[142:145], v[224:227], v[110:113]
	v_mfma_f32_16x16x32_bf16 v[106:109], v[156:159], v[224:227], v[106:109]
	v_mfma_f32_16x16x32_bf16 v[94:97], v[142:145], v[232:235], v[94:97]
	v_mfma_f32_16x16x32_bf16 v[90:93], v[156:159], v[232:235], v[90:93]
	v_mfma_f32_16x16x32_bf16 v[78:81], v[142:145], v[240:243], v[78:81]
	v_mfma_f32_16x16x32_bf16 v[74:77], v[156:159], v[240:243], v[74:77]
	v_mfma_f32_16x16x32_bf16 v[126:129], v[152:155], v[220:223], v[126:129]
	v_mfma_f32_16x16x32_bf16 v[122:125], v[160:163], v[220:223], v[122:125]
	v_mfma_f32_16x16x32_bf16 v[110:113], v[152:155], v[228:231], v[110:113]
	v_mfma_f32_16x16x32_bf16 v[106:109], v[160:163], v[228:231], v[106:109]
	v_mfma_f32_16x16x32_bf16 v[94:97], v[152:155], v[236:239], v[94:97]
	v_mfma_f32_16x16x32_bf16 v[90:93], v[160:163], v[236:239], v[90:93]
	v_mfma_f32_16x16x32_bf16 v[78:81], v[152:155], v[244:247], v[78:81]
	v_mfma_f32_16x16x32_bf16 v[74:77], v[160:163], v[244:247], v[74:77]
	s_setprio 0
	s_setprio 1
	v_mfma_f32_16x16x32_bf16 v[118:121], v[164:167], v[212:215], v[118:121]
	v_mfma_f32_16x16x32_bf16 v[114:117], v[190:193], v[212:215], v[114:117]
	v_mfma_f32_16x16x32_bf16 v[102:105], v[164:167], v[224:227], v[102:105]
	v_mfma_f32_16x16x32_bf16 v[98:101], v[190:193], v[224:227], v[98:101]
	v_mfma_f32_16x16x32_bf16 v[86:89], v[164:167], v[232:235], v[86:89]
	v_mfma_f32_16x16x32_bf16 v[82:85], v[190:193], v[232:235], v[82:85]
	v_mfma_f32_16x16x32_bf16 v[70:73], v[164:167], v[240:243], v[70:73]
	v_mfma_f32_16x16x32_bf16 v[66:69], v[190:193], v[240:243], v[66:69]
	v_mfma_f32_16x16x32_bf16 v[118:121], v[186:189], v[220:223], v[118:121]
	v_mfma_f32_16x16x32_bf16 v[114:117], v[194:197], v[220:223], v[114:117]
	v_mfma_f32_16x16x32_bf16 v[102:105], v[186:189], v[228:231], v[102:105]
	v_mfma_f32_16x16x32_bf16 v[98:101], v[194:197], v[228:231], v[98:101]
	v_mfma_f32_16x16x32_bf16 v[86:89], v[186:189], v[236:239], v[86:89]
	v_mfma_f32_16x16x32_bf16 v[82:85], v[194:197], v[236:239], v[82:85]
	v_mfma_f32_16x16x32_bf16 v[70:73], v[186:189], v[244:247], v[70:73]
	v_mfma_f32_16x16x32_bf16 v[66:69], v[194:197], v[244:247], v[66:69]
	s_barrier
; #define PG8_STAGE(bufoff, gbase, voff) do { _Pragma("unroll") for (int _i = 0; _i < 2; ++_i) \
;         __builtin_amdgcn_global_load_lds((const unsigned*)((const char*)(gbase) + (voff)[_i]), (PG8_LAS unsigned*)(lds + (bufoff) + ldsw + _i * 8192), 16, 0, 0); } while (0)
; #define PG8_LDA(dst, b, h) do { _Pragma("unroll") for (int m = 0; m < 4; ++m) _Pragma("unroll") for (int k = 0; k < 2; ++k) dst[m][k] = *(const PG8_LAS bf16x8*)(lds + PG8_SA(b, h) + aoff + m * 2048 + k * 1024); } while (0)
; #define PG8_MMA(ai, bj, At, Bt) do { __builtin_amdgcn_s_setprio(1); _Pragma("unroll") for (int m = 0; m < 4; ++m) _Pragma("unroll") for (int n = 0; n < 2; ++n) _Pragma("unroll") for (int k = 0; k < 2; ++k) \
;         acc[ai][bj][m][n] = __builtin_amdgcn_mfma_f32_16x16x32_bf16(Bt[n][k], At[m][k], acc[ai][bj][m][n], 0, 0, 0); __builtin_amdgcn_s_setprio(0); } while (0)
; #define PG8_WAIT_V(n) asm volatile("s_waitcnt vmcnt(" #n ")" ::: "memory")
; #define PG8_WAIT_L(n) asm volatile("s_waitcnt lgkmcnt(" #n ")" ::: "memory")
; #define PG8_BAR __builtin_amdgcn_s_barrier()
; #define PG8_SCHED __builtin_amdgcn_sched_barrier(0)
; template <class Epi, class Sched, bool ALIGN_EPI = false, bool SP2 = false>
; __device__ __forceinline__ void gemm_phase(PG8_LAS unsigned char* lds, const Gemm g, const Sched& S, const Epi& E, int tid_in) {
;     ...
;         for (int t = 0; t < nt; t += 2) {
;     ...
;             PG8_LDA(At, 1, 1); PG8_STAGE(PG8_SB(1, 0), b3, voffB); PG8_STAGE(PG8_SB(1, 1), b3 + hstep, voffB); PG8_STAGE(PG8_SA(1, 0), a3, voffA);
;             PG8_WAIT_V(8); PG8_WAIT_L(0); PG8_BAR; PG8_MMA(1, 0, At, B0); PG8_MMA(1, 1, At, B1); PG8_BAR; PG8_SCHED;
	s_setprio 0
	s_add_i32 s30, s60, s39
	v_lshl_add_u64 v[146:147], v[146:147], 0, s[74:75]
	s_mov_b32 m0, s30
	ds_read_b128 v[212:215], v151 offset:49152
	ds_read_b128 v[220:223], v151 offset:50176
	ds_read_b128 v[224:227], v151 offset:51200
	ds_read_b128 v[228:231], v151 offset:52224
	ds_read_b128 v[232:235], v151 offset:53248
	ds_read_b128 v[236:239], v151 offset:54272
	ds_read_b128 v[240:243], v151 offset:55296
	ds_read_b128 v[244:247], v151 offset:56320
	global_load_lds_dwordx4 v[146:147], off
	s_add_i32 m0, s30, 0x2000
	s_add_u32 s28, s28, 0x80080
	v_lshl_add_u64 v[146:147], v[168:169], 0, s[74:75]
	s_addc_u32 s29, s29, 0
	s_add_i32 s30, s61, s39
	global_load_lds_dwordx4 v[146:147], off
	v_lshl_add_u64 v[146:147], s[28:29], 0, v[134:135]
	s_mov_b32 m0, s30
	s_nop 0
	global_load_lds_dwordx4 v[146:147], off
	v_lshl_add_u64 v[146:147], s[28:29], 0, v[130:131]
	s_add_i32 m0, s30, 0x2000
	s_nop 0
	global_load_lds_dwordx4 v[146:147], off
	v_lshl_add_u64 v[146:147], v[216:217], 0, s[74:75]
	s_mov_b32 m0, s50
	s_nop 0
	global_load_lds_dwordx4 v[146:147], off
	v_lshl_add_u64 v[146:147], v[248:249], 0, s[74:75]
	s_mov_b32 m0, s51
	s_nop 0
	global_load_lds_dwordx4 v[146:147], off
	s_waitcnt vmcnt(8)
	s_waitcnt lgkmcnt(0)
	s_setprio 1
	s_barrier
	v_mfma_f32_16x16x32_bf16 v[62:65], v[142:145], v[212:215], v[62:65]
	v_mfma_f32_16x16x32_bf16 v[58:61], v[156:159], v[212:215], v[58:61]
	v_mfma_f32_16x16x32_bf16 v[46:49], v[142:145], v[224:227], v[46:49]
	v_mfma_f32_16x16x32_bf16 v[42:45], v[156:159], v[224:227], v[42:45]
	v_mfma_f32_16x16x32_bf16 v[28:31], v[142:145], v[232:235], v[28:31]
	v_mfma_f32_16x16x32_bf16 v[24:27], v[156:159], v[232:235], v[24:27]
	v_mfma_f32_16x16x32_bf16 v[12:15], v[142:145], v[240:243], v[12:15]
	v_mfma_f32_16x16x32_bf16 v[8:11], v[156:159], v[240:243], v[8:11]
	v_mfma_f32_16x16x32_bf16 v[62:65], v[152:155], v[220:223], v[62:65]
	v_mfma_f32_16x16x32_bf16 v[58:61], v[160:163], v[220:223], v[58:61]
	v_mfma_f32_16x16x32_bf16 v[46:49], v[152:155], v[228:231], v[46:49]
	v_mfma_f32_16x16x32_bf16 v[42:45], v[160:163], v[228:231], v[42:45]
	v_mfma_f32_16x16x32_bf16 v[28:31], v[152:155], v[236:239], v[28:31]
	v_mfma_f32_16x16x32_bf16 v[24:27], v[160:163], v[236:239], v[24:27]
	v_mfma_f32_16x16x32_bf16 v[12:15], v[152:155], v[244:247], v[12:15]
	v_mfma_f32_16x16x32_bf16 v[8:11], v[160:163], v[244:247], v[8:11]
	s_setprio 0
	s_setprio 1
	v_mfma_f32_16x16x32_bf16 v[54:57], v[164:167], v[212:215], v[54:57]
	v_mfma_f32_16x16x32_bf16 v[50:53], v[190:193], v[212:215], v[50:53]
	v_mfma_f32_16x16x32_bf16 v[38:41], v[164:167], v[224:227], v[38:41]
	v_mfma_f32_16x16x32_bf16 v[34:37], v[190:193], v[224:227], v[34:37]
	v_mfma_f32_16x16x32_bf16 v[20:23], v[164:167], v[232:235], v[20:23]
	v_mfma_f32_16x16x32_bf16 v[16:19], v[190:193], v[232:235], v[16:19]
	v_mfma_f32_16x16x32_bf16 v[4:7], v[164:167], v[240:243], v[4:7]
	v_mfma_f32_16x16x32_bf16 v[0:3], v[190:193], v[240:243], v[0:3]
	v_mfma_f32_16x16x32_bf16 v[54:57], v[186:189], v[220:223], v[54:57]
	v_mfma_f32_16x16x32_bf16 v[50:53], v[194:197], v[220:223], v[50:53]
	v_mfma_f32_16x16x32_bf16 v[38:41], v[186:189], v[228:231], v[38:41]
	v_mfma_f32_16x16x32_bf16 v[34:37], v[194:197], v[228:231], v[34:37]
	v_mfma_f32_16x16x32_bf16 v[20:23], v[186:189], v[236:239], v[20:23]
	v_mfma_f32_16x16x32_bf16 v[16:19], v[194:197], v[236:239], v[16:19]
	v_mfma_f32_16x16x32_bf16 v[4:7], v[186:189], v[244:247], v[4:7]
	v_mfma_f32_16x16x32_bf16 v[0:3], v[194:197], v[244:247], v[0:3]
	s_barrier
	s_setprio 0
	s_add_i32 s59, s59, 2
	s_add_u32 s6, s6, 0x100
	s_addc_u32 s7, s7, 0
	s_add_u32 s58, s58, 0x100
	s_addc_u32 s47, s47, 0
	s_cmp_gt_u32 s59, 29
	s_cbranch_scc0 .LBB0_59
	s_and_b64 vcc, exec, s[16:17]
	s_cbranch_vccz .LBB0_62
	s_barrier

; #define PG8_STAGE(bufoff, gbase, voff) do { _Pragma("unroll") for (int _i = 0; _i < 2; ++_i) \
;         __builtin_amdgcn_global_load_lds((const unsigned*)((const char*)(gbase) + (voff)[_i]), (PG8_LAS unsigned*)(lds + (bufoff) + ldsw + _i * 8192), 16, 0, 0); } while (0)
; #define PG8_LDA(dst, b, h) do { _Pragma("unroll") for (int m = 0; m < 4; ++m) _Pragma("unroll") for (int k = 0; k < 2; ++k) dst[m][k] = *(const PG8_LAS bf16x8*)(lds + PG8_SA(b, h) + aoff + m * 2048 + k * 1024); } while (0)
; #define PG8_LDB(dst, b, h) do { _Pragma("unroll") for (int n = 0; n < 2; ++n) _Pragma("unroll") for (int k = 0; k < 2; ++k) dst[n][k] = *(const PG8_LAS bf16x8*)(lds + PG8_SB(b, h) + boff + n * 2048 + k * 1024); } while (0)
; #define PG8_MMA(ai, bj, At, Bt) do { __builtin_amdgcn_s_setprio(1); _Pragma("unroll") for (int m = 0; m < 4; ++m) _Pragma("unroll") for (int n = 0; n < 2; ++n) _Pragma("unroll") for (int k = 0; k < 2; ++k) \
;         acc[ai][bj][m][n] = __builtin_amdgcn_mfma_f32_16x16x32_bf16(Bt[n][k], At[m][k], acc[ai][bj][m][n], 0, 0, 0); __builtin_amdgcn_s_setprio(0); } while (0)
; #define PG8_WAIT_V(n) asm volatile("s_waitcnt vmcnt(" #n ")" ::: "memory")
; #define PG8_WAIT_L(n) asm volatile("s_waitcnt lgkmcnt(" #n ")" ::: "memory")
; template <class Epi, class Sched, bool ALIGN_EPI = false, bool SP2 = false>
; __device__ __forceinline__ void gemm_phase(PG8_LAS unsigned char* lds, const Gemm g, const Sched& S, const Epi& E, int tid_in) {
;     ...
;             const bool last = (t == nt - 2);
;             const char* a1 = cA + (size_t)(t + 1) * kstep;
;             const char* a2 = last ? nA : cA + (size_t)(t + 2) * kstep; const char* b2 = last ? nB : cB + (size_t)(t + 2) * kstep;
;             const char* a3 = a2 + kstep; const char* b3 = b2 + kstep;
;             if (last && has_next) S.a_ready(nxt);
;             if constexpr (SP2) {
;             PG8_LDB(B0, 0, 0); PG8_LDB(B1, 0, 1); PG8_SCHED; PG8_LDA(At, 0, 0); PG8_STAGE(PG8_SA(1, 1), a1 + hstep, voffA);
;             PG8_WAIT_V(8); PG8_WAIT_L(0); PG8_BAR; PG8_MMA(0, 0, At, B0); PG8_MMA(0, 1, At, B1); PG8_BAR; PG8_SCHED;
;             PG8_LDA(At, 0, 1); PG8_STAGE(PG8_SB(0, 0), b2, voffB); PG8_STAGE(PG8_SB(0, 1), b2 + hstep, voffB); PG8_STAGE(PG8_SA(0, 0), a2, voffA);
;             PG8_WAIT_V(8); PG8_WAIT_L(0); PG8_BAR; PG8_MMA(1, 0, At, B0); PG8_MMA(1, 1, At, B1); PG8_BAR; PG8_SCHED;
.LBB0_349:
	s_add_u32 s26, s24, 0x100
	s_addc_u32 s27, s25, 0
	s_add_i32 s60, 0, 0x10000
	s_cmp_eq_u32 s59, 28
	s_cselect_b32 s31, s19, s27
	s_cselect_b32 s30, s45, s26
	s_cselect_b32 s29, s17, s58
	s_cselect_b32 s28, s57, s47
	s_add_i32 s61, 0, 0x14000
	v_add_u32_e32 v152, s60, v141
	v_add_u32_e32 v168, s61, v141
	ds_read_b128 v[136:139], v152
	ds_read_b128 v[144:147], v152 offset:1024
	ds_read_b128 v[148:151], v152 offset:2048
	ds_read_b128 v[152:155], v152 offset:3072
	ds_read_b128 v[156:159], v168
	ds_read_b128 v[160:163], v168 offset:1024
	ds_read_b128 v[164:167], v168 offset:2048
	ds_read_b128 v[186:189], v168 offset:3072
	v_lshl_add_u64 v[168:169], s[24:25], 0, v[132:133]
	s_add_i32 m0, s39, 0xc000
	ds_read_b128 v[190:193], v143
	ds_read_b128 v[194:197], v143 offset:1024
	ds_read_b128 v[212:215], v143 offset:2048
	ds_read_b128 v[220:223], v143 offset:3072
	ds_read_b128 v[224:227], v143 offset:4096
	ds_read_b128 v[228:231], v143 offset:5120
	ds_read_b128 v[232:235], v143 offset:6144
	ds_read_b128 v[236:239], v143 offset:7168
	global_load_lds_dwordx4 v[168:169], off
	v_lshl_add_u64 v[168:169], s[24:25], 0, v[134:135]
	s_add_i32 m0, s39, 0xe000
	s_nop 0
	global_load_lds_dwordx4 v[168:169], off
	s_waitcnt vmcnt(8)
	s_waitcnt lgkmcnt(0)
	s_setprio 1
	s_barrier
	v_mfma_f32_16x16x32_bf16 v[126:129], v[136:139], v[190:193], v[126:129]
	v_mfma_f32_16x16x32_bf16 v[122:125], v[148:151], v[190:193], v[122:125]
	v_mfma_f32_16x16x32_bf16 v[114:117], v[136:139], v[212:215], v[114:117]
	v_mfma_f32_16x16x32_bf16 v[110:113], v[148:151], v[212:215], v[110:113]
	v_mfma_f32_16x16x32_bf16 v[98:101], v[136:139], v[224:227], v[98:101]
	v_mfma_f32_16x16x32_bf16 v[94:97], v[148:151], v[224:227], v[94:97]
	v_mfma_f32_16x16x32_bf16 v[82:85], v[136:139], v[232:235], v[82:85]
	v_mfma_f32_16x16x32_bf16 v[78:81], v[148:151], v[232:235], v[78:81]
	v_mfma_f32_16x16x32_bf16 v[126:129], v[144:147], v[194:197], v[126:129]
	v_mfma_f32_16x16x32_bf16 v[122:125], v[152:155], v[194:197], v[122:125]
	v_mfma_f32_16x16x32_bf16 v[114:117], v[144:147], v[220:223], v[114:117]
	v_mfma_f32_16x16x32_bf16 v[110:113], v[152:155], v[220:223], v[110:113]
	v_mfma_f32_16x16x32_bf16 v[98:101], v[144:147], v[228:231], v[98:101]
	v_mfma_f32_16x16x32_bf16 v[94:97], v[152:155], v[228:231], v[94:97]
	v_mfma_f32_16x16x32_bf16 v[82:85], v[144:147], v[236:239], v[82:85]
	v_mfma_f32_16x16x32_bf16 v[78:81], v[152:155], v[236:239], v[78:81]
	s_setprio 0
	s_setprio 1
	v_mfma_f32_16x16x32_bf16 v[118:121], v[156:159], v[190:193], v[118:121]
	v_mfma_f32_16x16x32_bf16 v[106:109], v[164:167], v[190:193], v[106:109]
	v_mfma_f32_16x16x32_bf16 v[102:105], v[156:159], v[212:215], v[102:105]
	v_mfma_f32_16x16x32_bf16 v[90:93], v[164:167], v[212:215], v[90:93]
	v_mfma_f32_16x16x32_bf16 v[86:89], v[156:159], v[224:227], v[86:89]
	v_mfma_f32_16x16x32_bf16 v[74:77], v[164:167], v[224:227], v[74:77]
	v_mfma_f32_16x16x32_bf16 v[70:73], v[156:159], v[232:235], v[70:73]
	v_mfma_f32_16x16x32_bf16 v[66:69], v[164:167], v[232:235], v[66:69]
	v_mfma_f32_16x16x32_bf16 v[118:121], v[160:163], v[194:197], v[118:121]
	v_mfma_f32_16x16x32_bf16 v[106:109], v[186:189], v[194:197], v[106:109]
	v_mfma_f32_16x16x32_bf16 v[102:105], v[160:163], v[220:223], v[102:105]
	v_mfma_f32_16x16x32_bf16 v[90:93], v[186:189], v[220:223], v[90:93]
	v_mfma_f32_16x16x32_bf16 v[86:89], v[160:163], v[228:231], v[86:89]
	v_mfma_f32_16x16x32_bf16 v[74:77], v[186:189], v[228:231], v[74:77]
	v_mfma_f32_16x16x32_bf16 v[70:73], v[160:163], v[236:239], v[70:73]
	v_mfma_f32_16x16x32_bf16 v[66:69], v[186:189], v[236:239], v[66:69]
	s_barrier
	s_setprio 0
	s_add_i32 s24, s60, s4
	v_lshl_add_u64 v[168:169], s[28:29], 0, v[32:33]
	s_mov_b32 m0, s24
	ds_read_b128 v[190:193], v143 offset:16384
	ds_read_b128 v[194:197], v143 offset:17408
	ds_read_b128 v[212:215], v143 offset:18432
	ds_read_b128 v[220:223], v143 offset:19456
	ds_read_b128 v[224:227], v143 offset:20480
	ds_read_b128 v[228:231], v143 offset:21504
	ds_read_b128 v[232:235], v143 offset:22528
	ds_read_b128 v[236:239], v143 offset:23552
	global_load_lds_dwordx4 v[168:169], off
	s_add_i32 m0, s24, 0x2000
	s_add_u32 s24, s28, 0x80000
	v_lshl_add_u64 v[216:217], s[28:29], 0, v[130:131]
	s_addc_u32 s25, s29, 0
	s_add_i32 s60, s61, s4
	global_load_lds_dwordx4 v[216:217], off
	v_lshl_add_u64 v[240:241], s[24:25], 0, v[32:33]
	s_mov_b32 m0, s60
	v_lshl_add_u64 v[242:243], s[30:31], 0, v[130:131]
	global_load_lds_dwordx4 v[240:241], off
	v_lshl_add_u64 v[240:241], s[24:25], 0, v[130:131]
	s_add_i32 m0, s60, 0x2000
	s_nop 0
	global_load_lds_dwordx4 v[240:241], off
	v_lshl_add_u64 v[240:241], s[30:31], 0, v[32:33]
	s_mov_b32 m0, s39
	s_nop 0
	global_load_lds_dwordx4 v[240:241], off
	s_mov_b32 m0, s42
	s_nop 0
	global_load_lds_dwordx4 v[242:243], off
	s_waitcnt vmcnt(8)
	s_waitcnt lgkmcnt(0)
	s_setprio 1
	s_barrier
; #define PG8_STAGE(bufoff, gbase, voff) do { _Pragma("unroll") for (int _i = 0; _i < 2; ++_i) \
;         __builtin_amdgcn_global_load_lds((const unsigned*)((const char*)(gbase) + (voff)[_i]), (PG8_LAS unsigned*)(lds + (bufoff) + ldsw + _i * 8192), 16, 0, 0); } while (0)
; #define PG8_LDA(dst, b, h) do { _Pragma("unroll") for (int m = 0; m < 4; ++m) _Pragma("unroll") for (int k = 0; k < 2; ++k) dst[m][k] = *(const PG8_LAS bf16x8*)(lds + PG8_SA(b, h) + aoff + m * 2048 + k * 1024); } while (0)
; #define PG8_LDB(dst, b, h) do { _Pragma("unroll") for (int n = 0; n < 2; ++n) _Pragma("unroll") for (int k = 0; k < 2; ++k) dst[n][k] = *(const PG8_LAS bf16x8*)(lds + PG8_SB(b, h) + boff + n * 2048 + k * 1024); } while (0)
; #define PG8_MMA(ai, bj, At, Bt) do { __builtin_amdgcn_s_setprio(1); _Pragma("unroll") for (int m = 0; m < 4; ++m) _Pragma("unroll") for (int n = 0; n < 2; ++n) _Pragma("unroll") for (int k = 0; k < 2; ++k) \
;         acc[ai][bj][m][n] = __builtin_amdgcn_mfma_f32_16x16x32_bf16(Bt[n][k], At[m][k], acc[ai][bj][m][n], 0, 0, 0); __builtin_amdgcn_s_setprio(0); } while (0)
; #define PG8_WAIT_V(n) asm volatile("s_waitcnt vmcnt(" #n ")" ::: "memory")
; #define PG8_WAIT_L(n) asm volatile("s_waitcnt lgkmcnt(" #n ")" ::: "memory")
; #define PG8_BAR __builtin_amdgcn_s_barrier()
; #define PG8_SCHED __builtin_amdgcn_sched_barrier(0)
; template <class Epi, class Sched, bool ALIGN_EPI = false, bool SP2 = false>
; __device__ __forceinline__ void gemm_phase(PG8_LAS unsigned char* lds, const Gemm g, const Sched& S, const Epi& E, int tid_in) {
;     ...
;             PG8_WAIT_V(8); PG8_WAIT_L(0); PG8_BAR; PG8_MMA(1, 0, At, B0); PG8_MMA(1, 1, At, B1); PG8_BAR; PG8_SCHED;
;             PG8_LDB(B0, 1, 0); PG8_LDB(B1, 1, 1); PG8_SCHED; PG8_LDA(At, 1, 0); PG8_STAGE(PG8_SA(0, 1), a2 + hstep, voffA);
;             PG8_WAIT_V(8); PG8_WAIT_L(0); PG8_BAR; PG8_MMA(0, 0, At, B0); PG8_MMA(0, 1, At, B1); PG8_BAR; PG8_SCHED;
	v_mfma_f32_16x16x32_bf16 v[62:65], v[136:139], v[190:193], v[62:65]
	v_mfma_f32_16x16x32_bf16 v[58:61], v[148:151], v[190:193], v[58:61]
	v_mfma_f32_16x16x32_bf16 v[50:53], v[136:139], v[212:215], v[50:53]
	v_mfma_f32_16x16x32_bf16 v[46:49], v[148:151], v[212:215], v[46:49]
	v_mfma_f32_16x16x32_bf16 v[34:37], v[136:139], v[224:227], v[34:37]
	v_mfma_f32_16x16x32_bf16 v[28:31], v[148:151], v[224:227], v[28:31]
	v_mfma_f32_16x16x32_bf16 v[16:19], v[136:139], v[232:235], v[16:19]
	v_mfma_f32_16x16x32_bf16 v[12:15], v[148:151], v[232:235], v[12:15]
	v_mfma_f32_16x16x32_bf16 v[62:65], v[144:147], v[194:197], v[62:65]
	v_mfma_f32_16x16x32_bf16 v[58:61], v[152:155], v[194:197], v[58:61]
	v_mfma_f32_16x16x32_bf16 v[50:53], v[144:147], v[220:223], v[50:53]
	v_mfma_f32_16x16x32_bf16 v[46:49], v[152:155], v[220:223], v[46:49]
	v_mfma_f32_16x16x32_bf16 v[34:37], v[144:147], v[228:231], v[34:37]
	v_mfma_f32_16x16x32_bf16 v[28:31], v[152:155], v[228:231], v[28:31]
	v_mfma_f32_16x16x32_bf16 v[16:19], v[144:147], v[236:239], v[16:19]
	v_mfma_f32_16x16x32_bf16 v[12:15], v[152:155], v[236:239], v[12:15]
	s_setprio 0
	s_setprio 1
	v_mfma_f32_16x16x32_bf16 v[54:57], v[156:159], v[190:193], v[54:57]
	v_mfma_f32_16x16x32_bf16 v[42:45], v[164:167], v[190:193], v[42:45]
	v_mfma_f32_16x16x32_bf16 v[38:41], v[156:159], v[212:215], v[38:41]
	v_mfma_f32_16x16x32_bf16 v[24:27], v[164:167], v[212:215], v[24:27]
	v_mfma_f32_16x16x32_bf16 v[20:23], v[156:159], v[224:227], v[20:23]
	v_mfma_f32_16x16x32_bf16 v[8:11], v[164:167], v[224:227], v[8:11]
	v_mfma_f32_16x16x32_bf16 v[4:7], v[156:159], v[232:235], v[4:7]
	v_mfma_f32_16x16x32_bf16 v[0:3], v[164:167], v[232:235], v[0:3]
	v_mfma_f32_16x16x32_bf16 v[54:57], v[160:163], v[194:197], v[54:57]
	v_mfma_f32_16x16x32_bf16 v[42:45], v[186:189], v[194:197], v[42:45]
	v_mfma_f32_16x16x32_bf16 v[38:41], v[160:163], v[220:223], v[38:41]
	v_mfma_f32_16x16x32_bf16 v[24:27], v[186:189], v[220:223], v[24:27]
	v_mfma_f32_16x16x32_bf16 v[20:23], v[160:163], v[228:231], v[20:23]
	v_mfma_f32_16x16x32_bf16 v[8:11], v[186:189], v[228:231], v[8:11]
	v_mfma_f32_16x16x32_bf16 v[4:7], v[160:163], v[236:239], v[4:7]
	v_mfma_f32_16x16x32_bf16 v[0:3], v[186:189], v[236:239], v[0:3]
	s_barrier
	s_setprio 0
	s_add_i32 s60, 0, 0x18000
	s_add_i32 s61, 0, 0x1c000
	v_add_u32_e32 v152, s60, v141
	v_add_u32_e32 v170, s61, v141
	ds_read_b128 v[136:139], v152
	ds_read_b128 v[144:147], v152 offset:1024
	ds_read_b128 v[148:151], v152 offset:2048
	ds_read_b128 v[152:155], v152 offset:3072
	ds_read_b128 v[156:159], v170
	ds_read_b128 v[160:163], v170 offset:1024
	ds_read_b128 v[164:167], v170 offset:2048
	ds_read_b128 v[186:189], v170 offset:3072
	s_add_u32 s24, s30, 0x80000
	s_addc_u32 s25, s31, 0
	s_mov_b32 m0, s43
	v_lshl_add_u64 v[244:245], s[24:25], 0, v[32:33]
	ds_read_b128 v[190:193], v143 offset:32768
	ds_read_b128 v[194:197], v143 offset:33792
	ds_read_b128 v[212:215], v143 offset:34816
	ds_read_b128 v[220:223], v143 offset:35840
	ds_read_b128 v[224:227], v143 offset:36864
	ds_read_b128 v[228:231], v143 offset:37888
	ds_read_b128 v[232:235], v143 offset:38912
	ds_read_b128 v[236:239], v143 offset:39936
	global_load_lds_dwordx4 v[244:245], off
	v_lshl_add_u64 v[244:245], s[24:25], 0, v[130:131]
	s_mov_b32 m0, s48
	s_nop 0
	global_load_lds_dwordx4 v[244:245], off
	s_waitcnt vmcnt(8)
	s_waitcnt lgkmcnt(0)
	s_setprio 1
	s_barrier
	v_mfma_f32_16x16x32_bf16 v[126:129], v[136:139], v[190:193], v[126:129]
	v_mfma_f32_16x16x32_bf16 v[122:125], v[148:151], v[190:193], v[122:125]
	v_mfma_f32_16x16x32_bf16 v[114:117], v[136:139], v[212:215], v[114:117]
	v_mfma_f32_16x16x32_bf16 v[110:113], v[148:151], v[212:215], v[110:113]
	v_mfma_f32_16x16x32_bf16 v[98:101], v[136:139], v[224:227], v[98:101]
	v_mfma_f32_16x16x32_bf16 v[94:97], v[148:151], v[224:227], v[94:97]
	v_mfma_f32_16x16x32_bf16 v[82:85], v[136:139], v[232:235], v[82:85]
	v_mfma_f32_16x16x32_bf16 v[78:81], v[148:151], v[232:235], v[78:81]
	v_mfma_f32_16x16x32_bf16 v[126:129], v[144:147], v[194:197], v[126:129]
	v_mfma_f32_16x16x32_bf16 v[122:125], v[152:155], v[194:197], v[122:125]
	v_mfma_f32_16x16x32_bf16 v[114:117], v[144:147], v[220:223], v[114:117]
	v_mfma_f32_16x16x32_bf16 v[110:113], v[152:155], v[220:223], v[110:113]
	v_mfma_f32_16x16x32_bf16 v[98:101], v[144:147], v[228:231], v[98:101]
	v_mfma_f32_16x16x32_bf16 v[94:97], v[152:155], v[228:231], v[94:97]
	v_mfma_f32_16x16x32_bf16 v[82:85], v[144:147], v[236:239], v[82:85]
	v_mfma_f32_16x16x32_bf16 v[78:81], v[152:155], v[236:239], v[78:81]
	s_setprio 0
	s_setprio 1
	v_mfma_f32_16x16x32_bf16 v[118:121], v[156:159], v[190:193], v[118:121]
	v_mfma_f32_16x16x32_bf16 v[106:109], v[164:167], v[190:193], v[106:109]
	v_mfma_f32_16x16x32_bf16 v[102:105], v[156:159], v[212:215], v[102:105]
	v_mfma_f32_16x16x32_bf16 v[90:93], v[164:167], v[212:215], v[90:93]
	v_mfma_f32_16x16x32_bf16 v[86:89], v[156:159], v[224:227], v[86:89]
	v_mfma_f32_16x16x32_bf16 v[74:77], v[164:167], v[224:227], v[74:77]
	v_mfma_f32_16x16x32_bf16 v[70:73], v[156:159], v[232:235], v[70:73]
	v_mfma_f32_16x16x32_bf16 v[66:69], v[164:167], v[232:235], v[66:69]
	v_mfma_f32_16x16x32_bf16 v[118:121], v[160:163], v[194:197], v[118:121]
	v_mfma_f32_16x16x32_bf16 v[106:109], v[186:189], v[194:197], v[106:109]
	v_mfma_f32_16x16x32_bf16 v[102:105], v[160:163], v[220:223], v[102:105]
	v_mfma_f32_16x16x32_bf16 v[90:93], v[186:189], v[220:223], v[90:93]
	v_mfma_f32_16x16x32_bf16 v[86:89], v[160:163], v[228:231], v[86:89]
	v_mfma_f32_16x16x32_bf16 v[74:77], v[186:189], v[228:231], v[74:77]
	v_mfma_f32_16x16x32_bf16 v[70:73], v[160:163], v[236:239], v[70:73]
	v_mfma_f32_16x16x32_bf16 v[66:69], v[186:189], v[236:239], v[66:69]
	s_barrier
; #define PG8_STAGE(bufoff, gbase, voff) do { _Pragma("unroll") for (int _i = 0; _i < 2; ++_i) \
;         __builtin_amdgcn_global_load_lds((const unsigned*)((const char*)(gbase) + (voff)[_i]), (PG8_LAS unsigned*)(lds + (bufoff) + ldsw + _i * 8192), 16, 0, 0); } while (0)
; #define PG8_LDA(dst, b, h) do { _Pragma("unroll") for (int m = 0; m < 4; ++m) _Pragma("unroll") for (int k = 0; k < 2; ++k) dst[m][k] = *(const PG8_LAS bf16x8*)(lds + PG8_SA(b, h) + aoff + m * 2048 + k * 1024); } while (0)
; #define PG8_MMA(ai, bj, At, Bt) do { __builtin_amdgcn_s_setprio(1); _Pragma("unroll") for (int m = 0; m < 4; ++m) _Pragma("unroll") for (int n = 0; n < 2; ++n) _Pragma("unroll") for (int k = 0; k < 2; ++k) \
;         acc[ai][bj][m][n] = __builtin_amdgcn_mfma_f32_16x16x32_bf16(Bt[n][k], At[m][k], acc[ai][bj][m][n], 0, 0, 0); __builtin_amdgcn_s_setprio(0); } while (0)
; #define PG8_WAIT_V(n) asm volatile("s_waitcnt vmcnt(" #n ")" ::: "memory")
; #define PG8_WAIT_L(n) asm volatile("s_waitcnt lgkmcnt(" #n ")" ::: "memory")
; #define PG8_BAR __builtin_amdgcn_s_barrier()
; #define PG8_SCHED __builtin_amdgcn_sched_barrier(0)
; template <class Epi, class Sched, bool ALIGN_EPI = false, bool SP2 = false>
; __device__ __forceinline__ void gemm_phase(PG8_LAS unsigned char* lds, const Gemm g, const Sched& S, const Epi& E, int tid_in) {
;     ...
;         for (int t = 0; t < nt; t += 2) {
;     ...
;             PG8_LDA(At, 1, 1); PG8_STAGE(PG8_SB(1, 0), b3, voffB); PG8_STAGE(PG8_SB(1, 1), b3 + hstep, voffB); PG8_STAGE(PG8_SA(1, 0), a3, voffA);
;             PG8_WAIT_V(8); PG8_WAIT_L(0); PG8_BAR; PG8_MMA(1, 0, At, B0); PG8_MMA(1, 1, At, B1); PG8_BAR; PG8_SCHED;
	s_setprio 0
	s_add_i32 s24, s60, s4
	v_lshl_add_u64 v[168:169], v[168:169], 0, s[74:75]
	s_mov_b32 m0, s24
	ds_read_b128 v[190:193], v143 offset:49152
	ds_read_b128 v[194:197], v143 offset:50176
	ds_read_b128 v[212:215], v143 offset:51200
	ds_read_b128 v[220:223], v143 offset:52224
	ds_read_b128 v[224:227], v143 offset:53248
	ds_read_b128 v[228:231], v143 offset:54272
	ds_read_b128 v[232:235], v143 offset:55296
	ds_read_b128 v[236:239], v143 offset:56320
	global_load_lds_dwordx4 v[168:169], off
	s_add_i32 m0, s24, 0x2000
	s_add_u32 s24, s28, 0x80080
	v_lshl_add_u64 v[168:169], v[216:217], 0, s[74:75]
	s_addc_u32 s25, s29, 0
	s_add_i32 s28, s61, s4
	global_load_lds_dwordx4 v[168:169], off
	v_lshl_add_u64 v[168:169], s[24:25], 0, v[32:33]
	s_mov_b32 m0, s28
	s_nop 0
	global_load_lds_dwordx4 v[168:169], off
	v_lshl_add_u64 v[168:169], s[24:25], 0, v[130:131]
	s_add_i32 m0, s28, 0x2000
	s_nop 0
	global_load_lds_dwordx4 v[168:169], off
	v_lshl_add_u64 v[168:169], v[240:241], 0, s[74:75]
	s_mov_b32 m0, s49
	s_nop 0
	global_load_lds_dwordx4 v[168:169], off
	v_lshl_add_u64 v[168:169], v[242:243], 0, s[74:75]
	s_mov_b32 m0, s51
	s_nop 0
	global_load_lds_dwordx4 v[168:169], off
	s_waitcnt vmcnt(8)
	s_waitcnt lgkmcnt(0)
	s_setprio 1
	s_barrier
	v_mfma_f32_16x16x32_bf16 v[62:65], v[136:139], v[190:193], v[62:65]
	v_mfma_f32_16x16x32_bf16 v[58:61], v[148:151], v[190:193], v[58:61]
	v_mfma_f32_16x16x32_bf16 v[50:53], v[136:139], v[212:215], v[50:53]
	v_mfma_f32_16x16x32_bf16 v[46:49], v[148:151], v[212:215], v[46:49]
	v_mfma_f32_16x16x32_bf16 v[34:37], v[136:139], v[224:227], v[34:37]
	v_mfma_f32_16x16x32_bf16 v[28:31], v[148:151], v[224:227], v[28:31]
	v_mfma_f32_16x16x32_bf16 v[16:19], v[136:139], v[232:235], v[16:19]
	v_mfma_f32_16x16x32_bf16 v[12:15], v[148:151], v[232:235], v[12:15]
	v_mfma_f32_16x16x32_bf16 v[62:65], v[144:147], v[194:197], v[62:65]
	v_mfma_f32_16x16x32_bf16 v[58:61], v[152:155], v[194:197], v[58:61]
	v_mfma_f32_16x16x32_bf16 v[50:53], v[144:147], v[220:223], v[50:53]
	v_mfma_f32_16x16x32_bf16 v[46:49], v[152:155], v[220:223], v[46:49]
	v_mfma_f32_16x16x32_bf16 v[34:37], v[144:147], v[228:231], v[34:37]
	v_mfma_f32_16x16x32_bf16 v[28:31], v[152:155], v[228:231], v[28:31]
	v_mfma_f32_16x16x32_bf16 v[16:19], v[144:147], v[236:239], v[16:19]
	v_mfma_f32_16x16x32_bf16 v[12:15], v[152:155], v[236:239], v[12:15]
	s_setprio 0
	s_setprio 1
	v_mfma_f32_16x16x32_bf16 v[54:57], v[156:159], v[190:193], v[54:57]
	v_mfma_f32_16x16x32_bf16 v[42:45], v[164:167], v[190:193], v[42:45]
	v_mfma_f32_16x16x32_bf16 v[38:41], v[156:159], v[212:215], v[38:41]
	v_mfma_f32_16x16x32_bf16 v[24:27], v[164:167], v[212:215], v[24:27]
	v_mfma_f32_16x16x32_bf16 v[20:23], v[156:159], v[224:227], v[20:23]
	v_mfma_f32_16x16x32_bf16 v[8:11], v[164:167], v[224:227], v[8:11]
	v_mfma_f32_16x16x32_bf16 v[4:7], v[156:159], v[232:235], v[4:7]
	v_mfma_f32_16x16x32_bf16 v[0:3], v[164:167], v[232:235], v[0:3]
	v_mfma_f32_16x16x32_bf16 v[54:57], v[160:163], v[194:197], v[54:57]
	v_mfma_f32_16x16x32_bf16 v[42:45], v[186:189], v[194:197], v[42:45]
	v_mfma_f32_16x16x32_bf16 v[38:41], v[160:163], v[220:223], v[38:41]
	v_mfma_f32_16x16x32_bf16 v[24:27], v[186:189], v[220:223], v[24:27]
	v_mfma_f32_16x16x32_bf16 v[20:23], v[160:163], v[228:231], v[20:23]
	v_mfma_f32_16x16x32_bf16 v[8:11], v[186:189], v[228:231], v[8:11]
	v_mfma_f32_16x16x32_bf16 v[4:7], v[160:163], v[236:239], v[4:7]
	v_mfma_f32_16x16x32_bf16 v[0:3], v[186:189], v[236:239], v[0:3]
	s_barrier
	s_setprio 0
	s_add_i32 s59, s59, 2
	s_add_u32 s47, s47, 0x100
	s_addc_u32 s58, s58, 0
	s_cmp_gt_u32 s59, 29
	s_mov_b64 s[24:25], s[26:27]
	s_cbranch_scc0 .LBB0_349
	s_and_b64 vcc, exec, s[14:15]
	s_cbranch_vccz .LBB0_352
	s_barrier

; #define PG8_STAGE(bufoff, gbase, voff) do { _Pragma("unroll") for (int _i = 0; _i < 2; ++_i) \
;         __builtin_amdgcn_global_load_lds((const unsigned*)((const char*)(gbase) + (voff)[_i]), (PG8_LAS unsigned*)(lds + (bufoff) + ldsw + _i * 8192), 16, 0, 0); } while (0)
; #define PG8_LDA(dst, b, h) do { _Pragma("unroll") for (int m = 0; m < 4; ++m) _Pragma("unroll") for (int k = 0; k < 2; ++k) dst[m][k] = *(const PG8_LAS bf16x8*)(lds + PG8_SA(b, h) + aoff + m * 2048 + k * 1024); } while (0)
; #define PG8_LDB(dst, b, h) do { _Pragma("unroll") for (int n = 0; n < 2; ++n) _Pragma("unroll") for (int k = 0; k < 2; ++k) dst[n][k] = *(const PG8_LAS bf16x8*)(lds + PG8_SB(b, h) + boff + n * 2048 + k * 1024); } while (0)
; #define PG8_MMA(ai, bj, At, Bt) do { __builtin_amdgcn_s_setprio(1); _Pragma("unroll") for (int m = 0; m < 4; ++m) _Pragma("unroll") for (int n = 0; n < 2; ++n) _Pragma("unroll") for (int k = 0; k < 2; ++k) \
;         acc[ai][bj][m][n] = __builtin_amdgcn_mfma_f32_16x16x32_bf16(Bt[n][k], At[m][k], acc[ai][bj][m][n], 0, 0, 0); __builtin_amdgcn_s_setprio(0); } while (0)
; #define PG8_WAIT_V(n) asm volatile("s_waitcnt vmcnt(" #n ")" ::: "memory")
; #define PG8_WAIT_L(n) asm volatile("s_waitcnt lgkmcnt(" #n ")" ::: "memory")
; template <class Epi, class Sched, bool ALIGN_EPI = false, bool SP2 = false>
; __device__ __forceinline__ void gemm_phase(PG8_LAS unsigned char* lds, const Gemm g, const Sched& S, const Epi& E, int tid_in) {
;     ...
;             const bool last = (t == nt - 2);
;             const char* a1 = cA + (size_t)(t + 1) * kstep;
;             const char* a2 = last ? nA : cA + (size_t)(t + 2) * kstep; const char* b2 = last ? nB : cB + (size_t)(t + 2) * kstep;
;             const char* a3 = a2 + kstep; const char* b3 = b2 + kstep;
;             if (last && has_next) S.a_ready(nxt);
;             if constexpr (SP2) {
;             PG8_LDB(B0, 0, 0); PG8_LDB(B1, 0, 1); PG8_SCHED; PG8_LDA(At, 0, 0); PG8_STAGE(PG8_SA(1, 1), a1 + hstep, voffA);
;             PG8_WAIT_V(8); PG8_WAIT_L(0); PG8_BAR; PG8_MMA(0, 0, At, B0); PG8_MMA(0, 1, At, B1); PG8_BAR; PG8_SCHED;
;             PG8_LDA(At, 0, 1); PG8_STAGE(PG8_SB(0, 0), b2, voffB); PG8_STAGE(PG8_SB(0, 1), b2 + hstep, voffB); PG8_STAGE(PG8_SA(0, 0), a2, voffA);
;             PG8_WAIT_V(8); PG8_WAIT_L(0); PG8_BAR; PG8_MMA(1, 0, At, B0); PG8_MMA(1, 1, At, B1); PG8_BAR; PG8_SCHED;
.LBB0_479:
	s_add_u32 s16, s56, 0xfff80080
	s_addc_u32 s17, s57, -1
	s_add_i32 s18, 0, 0x10000
	s_cmp_eq_u32 s82, 28
	s_cselect_b32 s63, s71, s17
	s_cselect_b32 s62, vcc_lo, s16
	s_cselect_b32 s61, s59, s77
	s_cselect_b32 s60, vcc_hi, s47
	s_add_i32 s19, 0, 0x14000
	v_add_u32_e32 v78, s18, v172
	v_add_u32_e32 v102, s19, v172
	ds_read_b128 v[66:69], v78
	ds_read_b128 v[70:73], v78 offset:1024
	ds_read_b128 v[74:77], v78 offset:2048
	ds_read_b128 v[78:81], v78 offset:3072
	ds_read_b128 v[86:89], v102
	ds_read_b128 v[90:93], v102 offset:1024
	ds_read_b128 v[94:97], v102 offset:2048
	ds_read_b128 v[102:105], v102 offset:3072
	v_lshl_add_u64 v[196:197], s[56:57], 0, v[192:193]
	s_add_i32 m0, s68, 0xc000
	ds_read_b128 v[162:165], v217
	ds_read_b128 v[166:169], v217 offset:1024
	ds_read_b128 v[220:223], v217 offset:2048
	ds_read_b128 v[224:227], v217 offset:3072
	ds_read_b128 v[228:231], v217 offset:4096
	ds_read_b128 v[232:235], v217 offset:5120
	ds_read_b128 v[236:239], v217 offset:6144
	ds_read_b128 v[240:243], v217 offset:7168
	global_load_lds_dwordx4 v[196:197], off
	v_lshl_add_u64 v[196:197], s[56:57], 0, v[194:195]
	s_add_i32 m0, s68, 0xe000
	s_nop 0
	global_load_lds_dwordx4 v[196:197], off
	s_waitcnt vmcnt(8)
	s_waitcnt lgkmcnt(0)
	s_setprio 1
	s_barrier
	v_mfma_f32_16x16x32_bf16 v[150:153], v[66:69], v[162:165], v[150:153]
	v_mfma_f32_16x16x32_bf16 v[146:149], v[74:77], v[162:165], v[146:149]
	v_mfma_f32_16x16x32_bf16 v[138:141], v[66:69], v[220:223], v[138:141]
	v_mfma_f32_16x16x32_bf16 v[130:133], v[74:77], v[220:223], v[130:133]
	v_mfma_f32_16x16x32_bf16 v[122:125], v[66:69], v[228:231], v[122:125]
	v_mfma_f32_16x16x32_bf16 v[110:113], v[74:77], v[228:231], v[110:113]
	v_mfma_f32_16x16x32_bf16 v[114:117], v[66:69], v[236:239], v[114:117]
	v_mfma_f32_16x16x32_bf16 v[98:101], v[74:77], v[236:239], v[98:101]
	v_mfma_f32_16x16x32_bf16 v[150:153], v[70:73], v[166:169], v[150:153]
	v_mfma_f32_16x16x32_bf16 v[146:149], v[78:81], v[166:169], v[146:149]
	v_mfma_f32_16x16x32_bf16 v[138:141], v[70:73], v[224:227], v[138:141]
	v_mfma_f32_16x16x32_bf16 v[130:133], v[78:81], v[224:227], v[130:133]
	v_mfma_f32_16x16x32_bf16 v[122:125], v[70:73], v[232:235], v[122:125]
	v_mfma_f32_16x16x32_bf16 v[110:113], v[78:81], v[232:235], v[110:113]
	v_mfma_f32_16x16x32_bf16 v[114:117], v[70:73], v[240:243], v[114:117]
	v_mfma_f32_16x16x32_bf16 v[98:101], v[78:81], v[240:243], v[98:101]
	s_setprio 0
	s_setprio 1
	v_mfma_f32_16x16x32_bf16 v[158:161], v[86:89], v[162:165], v[158:161]
	v_mfma_f32_16x16x32_bf16 v[154:157], v[94:97], v[162:165], v[154:157]
	v_mfma_f32_16x16x32_bf16 v[142:145], v[86:89], v[220:223], v[142:145]
	v_mfma_f32_16x16x32_bf16 v[134:137], v[94:97], v[220:223], v[134:137]
	v_mfma_f32_16x16x32_bf16 v[126:129], v[86:89], v[228:231], v[126:129]
	v_mfma_f32_16x16x32_bf16 v[118:121], v[94:97], v[228:231], v[118:121]
	v_mfma_f32_16x16x32_bf16 v[106:109], v[86:89], v[236:239], v[106:109]
	v_mfma_f32_16x16x32_bf16 v[82:85], v[94:97], v[236:239], v[82:85]
	v_mfma_f32_16x16x32_bf16 v[158:161], v[90:93], v[166:169], v[158:161]
	v_mfma_f32_16x16x32_bf16 v[154:157], v[102:105], v[166:169], v[154:157]
	v_mfma_f32_16x16x32_bf16 v[142:145], v[90:93], v[224:227], v[142:145]
	v_mfma_f32_16x16x32_bf16 v[134:137], v[102:105], v[224:227], v[134:137]
	v_mfma_f32_16x16x32_bf16 v[126:129], v[90:93], v[232:235], v[126:129]
	v_mfma_f32_16x16x32_bf16 v[118:121], v[102:105], v[232:235], v[118:121]
	v_mfma_f32_16x16x32_bf16 v[106:109], v[90:93], v[240:243], v[106:109]
	v_mfma_f32_16x16x32_bf16 v[82:85], v[102:105], v[240:243], v[82:85]
	s_barrier
	s_setprio 0
	s_add_i32 s16, s18, s67
	v_lshl_add_u64 v[196:197], s[60:61], 0, v[32:33]
	s_mov_b32 m0, s16
	ds_read_b128 v[162:165], v217 offset:16384
	ds_read_b128 v[166:169], v217 offset:17408
	ds_read_b128 v[220:223], v217 offset:18432
	ds_read_b128 v[224:227], v217 offset:19456
	ds_read_b128 v[228:231], v217 offset:20480
	ds_read_b128 v[232:235], v217 offset:21504
	ds_read_b128 v[236:239], v217 offset:22528
	ds_read_b128 v[240:243], v217 offset:23552
	global_load_lds_dwordx4 v[196:197], off
	s_add_i32 m0, s16, 0x2000
	s_add_u32 s16, s60, 0x80000
	v_lshl_add_u64 v[244:245], s[60:61], 0, v[186:187]
	s_addc_u32 s17, s61, 0
	s_add_i32 s18, s19, s67
	global_load_lds_dwordx4 v[244:245], off
	v_lshl_add_u64 v[246:247], s[16:17], 0, v[32:33]
	s_mov_b32 m0, s18
	v_lshl_add_u64 v[248:249], s[62:63], 0, v[188:189]
	global_load_lds_dwordx4 v[246:247], off
	v_lshl_add_u64 v[246:247], s[16:17], 0, v[186:187]
	s_add_i32 m0, s18, 0x2000
	s_nop 0
	global_load_lds_dwordx4 v[246:247], off
	v_lshl_add_u64 v[246:247], s[62:63], 0, v[190:191]
	s_mov_b32 m0, s68
	s_nop 0
	global_load_lds_dwordx4 v[246:247], off
	s_mov_b32 m0, s14
	s_nop 0
	global_load_lds_dwordx4 v[248:249], off
	s_waitcnt vmcnt(8)
	s_waitcnt lgkmcnt(0)
	s_setprio 1
	s_barrier
; #define PG8_STAGE(bufoff, gbase, voff) do { _Pragma("unroll") for (int _i = 0; _i < 2; ++_i) \
;         __builtin_amdgcn_global_load_lds((const unsigned*)((const char*)(gbase) + (voff)[_i]), (PG8_LAS unsigned*)(lds + (bufoff) + ldsw + _i * 8192), 16, 0, 0); } while (0)
; #define PG8_LDA(dst, b, h) do { _Pragma("unroll") for (int m = 0; m < 4; ++m) _Pragma("unroll") for (int k = 0; k < 2; ++k) dst[m][k] = *(const PG8_LAS bf16x8*)(lds + PG8_SA(b, h) + aoff + m * 2048 + k * 1024); } while (0)
; #define PG8_LDB(dst, b, h) do { _Pragma("unroll") for (int n = 0; n < 2; ++n) _Pragma("unroll") for (int k = 0; k < 2; ++k) dst[n][k] = *(const PG8_LAS bf16x8*)(lds + PG8_SB(b, h) + boff + n * 2048 + k * 1024); } while (0)
; #define PG8_MMA(ai, bj, At, Bt) do { __builtin_amdgcn_s_setprio(1); _Pragma("unroll") for (int m = 0; m < 4; ++m) _Pragma("unroll") for (int n = 0; n < 2; ++n) _Pragma("unroll") for (int k = 0; k < 2; ++k) \
;         acc[ai][bj][m][n] = __builtin_amdgcn_mfma_f32_16x16x32_bf16(Bt[n][k], At[m][k], acc[ai][bj][m][n], 0, 0, 0); __builtin_amdgcn_s_setprio(0); } while (0)
; #define PG8_WAIT_V(n) asm volatile("s_waitcnt vmcnt(" #n ")" ::: "memory")
; #define PG8_WAIT_L(n) asm volatile("s_waitcnt lgkmcnt(" #n ")" ::: "memory")
; #define PG8_BAR __builtin_amdgcn_s_barrier()
; #define PG8_SCHED __builtin_amdgcn_sched_barrier(0)
; template <class Epi, class Sched, bool ALIGN_EPI = false, bool SP2 = false>
; __device__ __forceinline__ void gemm_phase(PG8_LAS unsigned char* lds, const Gemm g, const Sched& S, const Epi& E, int tid_in) {
;     ...
;             PG8_WAIT_V(8); PG8_WAIT_L(0); PG8_BAR; PG8_MMA(1, 0, At, B0); PG8_MMA(1, 1, At, B1); PG8_BAR; PG8_SCHED;
;             PG8_LDB(B0, 1, 0); PG8_LDB(B1, 1, 1); PG8_SCHED; PG8_LDA(At, 1, 0); PG8_STAGE(PG8_SA(0, 1), a2 + hstep, voffA);
;             PG8_WAIT_V(8); PG8_WAIT_L(0); PG8_BAR; PG8_MMA(0, 0, At, B0); PG8_MMA(0, 1, At, B1); PG8_BAR; PG8_SCHED;
	v_mfma_f32_16x16x32_bf16 v[54:57], v[66:69], v[162:165], v[54:57]
	v_mfma_f32_16x16x32_bf16 v[50:53], v[74:77], v[162:165], v[50:53]
	v_mfma_f32_16x16x32_bf16 v[42:45], v[66:69], v[220:223], v[42:45]
	v_mfma_f32_16x16x32_bf16 v[34:37], v[74:77], v[220:223], v[34:37]
	v_mfma_f32_16x16x32_bf16 v[24:27], v[66:69], v[228:231], v[24:27]
	v_mfma_f32_16x16x32_bf16 v[12:15], v[74:77], v[228:231], v[12:15]
	v_mfma_f32_16x16x32_bf16 v[16:19], v[66:69], v[236:239], v[16:19]
	v_mfma_f32_16x16x32_bf16 v[4:7], v[74:77], v[236:239], v[4:7]
	v_mfma_f32_16x16x32_bf16 v[54:57], v[70:73], v[166:169], v[54:57]
	v_mfma_f32_16x16x32_bf16 v[50:53], v[78:81], v[166:169], v[50:53]
	v_mfma_f32_16x16x32_bf16 v[42:45], v[70:73], v[224:227], v[42:45]
	v_mfma_f32_16x16x32_bf16 v[34:37], v[78:81], v[224:227], v[34:37]
	v_mfma_f32_16x16x32_bf16 v[24:27], v[70:73], v[232:235], v[24:27]
	v_mfma_f32_16x16x32_bf16 v[12:15], v[78:81], v[232:235], v[12:15]
	v_mfma_f32_16x16x32_bf16 v[16:19], v[70:73], v[240:243], v[16:19]
	v_mfma_f32_16x16x32_bf16 v[4:7], v[78:81], v[240:243], v[4:7]
	s_setprio 0
	s_setprio 1
	v_mfma_f32_16x16x32_bf16 v[62:65], v[86:89], v[162:165], v[62:65]
	v_mfma_f32_16x16x32_bf16 v[58:61], v[94:97], v[162:165], v[58:61]
	v_mfma_f32_16x16x32_bf16 v[46:49], v[86:89], v[220:223], v[46:49]
	v_mfma_f32_16x16x32_bf16 v[38:41], v[94:97], v[220:223], v[38:41]
	v_mfma_f32_16x16x32_bf16 v[28:31], v[86:89], v[228:231], v[28:31]
	v_mfma_f32_16x16x32_bf16 v[20:23], v[94:97], v[228:231], v[20:23]
	v_mfma_f32_16x16x32_bf16 v[8:11], v[86:89], v[236:239], v[8:11]
	v_mfma_f32_16x16x32_bf16 v[0:3], v[94:97], v[236:239], v[0:3]
	v_mfma_f32_16x16x32_bf16 v[62:65], v[90:93], v[166:169], v[62:65]
	v_mfma_f32_16x16x32_bf16 v[58:61], v[102:105], v[166:169], v[58:61]
	v_mfma_f32_16x16x32_bf16 v[46:49], v[90:93], v[224:227], v[46:49]
	v_mfma_f32_16x16x32_bf16 v[38:41], v[102:105], v[224:227], v[38:41]
	v_mfma_f32_16x16x32_bf16 v[28:31], v[90:93], v[232:235], v[28:31]
	v_mfma_f32_16x16x32_bf16 v[20:23], v[102:105], v[232:235], v[20:23]
	v_mfma_f32_16x16x32_bf16 v[8:11], v[90:93], v[240:243], v[8:11]
	v_mfma_f32_16x16x32_bf16 v[0:3], v[102:105], v[240:243], v[0:3]
	s_barrier
	s_setprio 0
	s_add_i32 s18, 0, 0x18000
	s_add_i32 s19, 0, 0x1c000
	v_add_u32_e32 v78, s18, v172
	v_add_u32_e32 v102, s19, v172
	ds_read_b128 v[66:69], v78
	ds_read_b128 v[70:73], v78 offset:1024
	ds_read_b128 v[74:77], v78 offset:2048
	ds_read_b128 v[78:81], v78 offset:3072
	ds_read_b128 v[86:89], v102
	ds_read_b128 v[90:93], v102 offset:1024
	ds_read_b128 v[94:97], v102 offset:2048
	ds_read_b128 v[102:105], v102 offset:3072
	s_add_u32 s16, s62, 0x80000
	s_addc_u32 s17, s63, 0
	s_mov_b32 m0, s15
	v_lshl_add_u64 v[250:251], s[16:17], 0, v[190:191]
	ds_read_b128 v[162:165], v217 offset:32768
	ds_read_b128 v[166:169], v217 offset:33792
	ds_read_b128 v[220:223], v217 offset:34816
	ds_read_b128 v[224:227], v217 offset:35840
	ds_read_b128 v[228:231], v217 offset:36864
	ds_read_b128 v[232:235], v217 offset:37888
	ds_read_b128 v[236:239], v217 offset:38912
	ds_read_b128 v[240:243], v217 offset:39936
	global_load_lds_dwordx4 v[250:251], off
	v_lshl_add_u64 v[250:251], s[16:17], 0, v[188:189]
	s_mov_b32 m0, s4
	s_nop 0
	global_load_lds_dwordx4 v[250:251], off
	s_waitcnt vmcnt(8)
	s_waitcnt lgkmcnt(0)
	s_setprio 1
	s_barrier
	v_mfma_f32_16x16x32_bf16 v[150:153], v[66:69], v[162:165], v[150:153]
	v_mfma_f32_16x16x32_bf16 v[146:149], v[74:77], v[162:165], v[146:149]
	v_mfma_f32_16x16x32_bf16 v[138:141], v[66:69], v[220:223], v[138:141]
	v_mfma_f32_16x16x32_bf16 v[130:133], v[74:77], v[220:223], v[130:133]
	v_mfma_f32_16x16x32_bf16 v[122:125], v[66:69], v[228:231], v[122:125]
	v_mfma_f32_16x16x32_bf16 v[110:113], v[74:77], v[228:231], v[110:113]
	v_mfma_f32_16x16x32_bf16 v[114:117], v[66:69], v[236:239], v[114:117]
	v_mfma_f32_16x16x32_bf16 v[98:101], v[74:77], v[236:239], v[98:101]
	v_mfma_f32_16x16x32_bf16 v[150:153], v[70:73], v[166:169], v[150:153]
	v_mfma_f32_16x16x32_bf16 v[146:149], v[78:81], v[166:169], v[146:149]
	v_mfma_f32_16x16x32_bf16 v[138:141], v[70:73], v[224:227], v[138:141]
	v_mfma_f32_16x16x32_bf16 v[130:133], v[78:81], v[224:227], v[130:133]
	v_mfma_f32_16x16x32_bf16 v[122:125], v[70:73], v[232:235], v[122:125]
	v_mfma_f32_16x16x32_bf16 v[110:113], v[78:81], v[232:235], v[110:113]
	v_mfma_f32_16x16x32_bf16 v[114:117], v[70:73], v[240:243], v[114:117]
	v_mfma_f32_16x16x32_bf16 v[98:101], v[78:81], v[240:243], v[98:101]
	s_setprio 0
	s_setprio 1
	v_mfma_f32_16x16x32_bf16 v[158:161], v[86:89], v[162:165], v[158:161]
	v_mfma_f32_16x16x32_bf16 v[154:157], v[94:97], v[162:165], v[154:157]
	v_mfma_f32_16x16x32_bf16 v[142:145], v[86:89], v[220:223], v[142:145]
	v_mfma_f32_16x16x32_bf16 v[134:137], v[94:97], v[220:223], v[134:137]
	v_mfma_f32_16x16x32_bf16 v[126:129], v[86:89], v[228:231], v[126:129]
	v_mfma_f32_16x16x32_bf16 v[118:121], v[94:97], v[228:231], v[118:121]
	v_mfma_f32_16x16x32_bf16 v[106:109], v[86:89], v[236:239], v[106:109]
	v_mfma_f32_16x16x32_bf16 v[82:85], v[94:97], v[236:239], v[82:85]
	v_mfma_f32_16x16x32_bf16 v[158:161], v[90:93], v[166:169], v[158:161]
	v_mfma_f32_16x16x32_bf16 v[154:157], v[102:105], v[166:169], v[154:157]
	v_mfma_f32_16x16x32_bf16 v[142:145], v[90:93], v[224:227], v[142:145]
	v_mfma_f32_16x16x32_bf16 v[134:137], v[102:105], v[224:227], v[134:137]
	v_mfma_f32_16x16x32_bf16 v[126:129], v[90:93], v[232:235], v[126:129]
	v_mfma_f32_16x16x32_bf16 v[118:121], v[102:105], v[232:235], v[118:121]
	v_mfma_f32_16x16x32_bf16 v[106:109], v[90:93], v[240:243], v[106:109]
	v_mfma_f32_16x16x32_bf16 v[82:85], v[102:105], v[240:243], v[82:85]
	s_barrier
; #define PG8_STAGE(bufoff, gbase, voff) do { _Pragma("unroll") for (int _i = 0; _i < 2; ++_i) \
;         __builtin_amdgcn_global_load_lds((const unsigned*)((const char*)(gbase) + (voff)[_i]), (PG8_LAS unsigned*)(lds + (bufoff) + ldsw + _i * 8192), 16, 0, 0); } while (0)
; #define PG8_LDA(dst, b, h) do { _Pragma("unroll") for (int m = 0; m < 4; ++m) _Pragma("unroll") for (int k = 0; k < 2; ++k) dst[m][k] = *(const PG8_LAS bf16x8*)(lds + PG8_SA(b, h) + aoff + m * 2048 + k * 1024); } while (0)
; #define PG8_MMA(ai, bj, At, Bt) do { __builtin_amdgcn_s_setprio(1); _Pragma("unroll") for (int m = 0; m < 4; ++m) _Pragma("unroll") for (int n = 0; n < 2; ++n) _Pragma("unroll") for (int k = 0; k < 2; ++k) \
;         acc[ai][bj][m][n] = __builtin_amdgcn_mfma_f32_16x16x32_bf16(Bt[n][k], At[m][k], acc[ai][bj][m][n], 0, 0, 0); __builtin_amdgcn_s_setprio(0); } while (0)
; #define PG8_WAIT_V(n) asm volatile("s_waitcnt vmcnt(" #n ")" ::: "memory")
; #define PG8_WAIT_L(n) asm volatile("s_waitcnt lgkmcnt(" #n ")" ::: "memory")
; #define PG8_BAR __builtin_amdgcn_s_barrier()
; #define PG8_SCHED __builtin_amdgcn_sched_barrier(0)
; template <class Epi, class Sched, bool ALIGN_EPI = false, bool SP2 = false>
; __device__ __forceinline__ void gemm_phase(PG8_LAS unsigned char* lds, const Gemm g, const Sched& S, const Epi& E, int tid_in) {
;     ...
;         for (int t = 0; t < nt; t += 2) {
;     ...
;             PG8_LDA(At, 1, 1); PG8_STAGE(PG8_SB(1, 0), b3, voffB); PG8_STAGE(PG8_SB(1, 1), b3 + hstep, voffB); PG8_STAGE(PG8_SA(1, 0), a3, voffA);
;             PG8_WAIT_V(8); PG8_WAIT_L(0); PG8_BAR; PG8_MMA(1, 0, At, B0); PG8_MMA(1, 1, At, B1); PG8_BAR; PG8_SCHED;
	s_setprio 0
	s_add_i32 s16, s18, s67
	v_lshl_add_u64 v[196:197], v[196:197], 0, s[74:75]
	s_mov_b32 m0, s16
	ds_read_b128 v[162:165], v217 offset:49152
	ds_read_b128 v[166:169], v217 offset:50176
	ds_read_b128 v[220:223], v217 offset:51200
	ds_read_b128 v[224:227], v217 offset:52224
	ds_read_b128 v[228:231], v217 offset:53248
	ds_read_b128 v[232:235], v217 offset:54272
	ds_read_b128 v[236:239], v217 offset:55296
	ds_read_b128 v[240:243], v217 offset:56320
	global_load_lds_dwordx4 v[196:197], off
	s_add_i32 m0, s16, 0x2000
	s_add_u32 s16, s60, 0x80080
	v_lshl_add_u64 v[196:197], v[244:245], 0, s[74:75]
	s_addc_u32 s17, s61, 0
	s_add_i32 s18, s19, s67
	global_load_lds_dwordx4 v[196:197], off
	v_lshl_add_u64 v[196:197], s[16:17], 0, v[32:33]
	s_mov_b32 m0, s18
	s_nop 0
	global_load_lds_dwordx4 v[196:197], off
	v_lshl_add_u64 v[196:197], s[16:17], 0, v[186:187]
	s_add_i32 m0, s18, 0x2000
	s_nop 0
	global_load_lds_dwordx4 v[196:197], off
	v_lshl_add_u64 v[196:197], v[246:247], 0, s[74:75]
	s_mov_b32 m0, s85
	s_nop 0
	global_load_lds_dwordx4 v[196:197], off
	v_lshl_add_u64 v[196:197], v[248:249], 0, s[74:75]
	s_mov_b32 m0, s80
	s_nop 0
	global_load_lds_dwordx4 v[196:197], off
	s_waitcnt vmcnt(8)
	s_waitcnt lgkmcnt(0)
	s_setprio 1
	s_barrier
	v_mfma_f32_16x16x32_bf16 v[54:57], v[66:69], v[162:165], v[54:57]
	v_mfma_f32_16x16x32_bf16 v[50:53], v[74:77], v[162:165], v[50:53]
	v_mfma_f32_16x16x32_bf16 v[42:45], v[66:69], v[220:223], v[42:45]
	v_mfma_f32_16x16x32_bf16 v[34:37], v[74:77], v[220:223], v[34:37]
	v_mfma_f32_16x16x32_bf16 v[24:27], v[66:69], v[228:231], v[24:27]
	v_mfma_f32_16x16x32_bf16 v[12:15], v[74:77], v[228:231], v[12:15]
	v_mfma_f32_16x16x32_bf16 v[16:19], v[66:69], v[236:239], v[16:19]
	v_mfma_f32_16x16x32_bf16 v[4:7], v[74:77], v[236:239], v[4:7]
	v_mfma_f32_16x16x32_bf16 v[54:57], v[70:73], v[166:169], v[54:57]
	v_mfma_f32_16x16x32_bf16 v[50:53], v[78:81], v[166:169], v[50:53]
	v_mfma_f32_16x16x32_bf16 v[42:45], v[70:73], v[224:227], v[42:45]
	v_mfma_f32_16x16x32_bf16 v[34:37], v[78:81], v[224:227], v[34:37]
	v_mfma_f32_16x16x32_bf16 v[24:27], v[70:73], v[232:235], v[24:27]
	v_mfma_f32_16x16x32_bf16 v[12:15], v[78:81], v[232:235], v[12:15]
	v_mfma_f32_16x16x32_bf16 v[16:19], v[70:73], v[240:243], v[16:19]
	v_mfma_f32_16x16x32_bf16 v[4:7], v[78:81], v[240:243], v[4:7]
	s_setprio 0
	s_setprio 1
	v_mfma_f32_16x16x32_bf16 v[62:65], v[86:89], v[162:165], v[62:65]
	v_mfma_f32_16x16x32_bf16 v[58:61], v[94:97], v[162:165], v[58:61]
	v_mfma_f32_16x16x32_bf16 v[46:49], v[86:89], v[220:223], v[46:49]
	v_mfma_f32_16x16x32_bf16 v[38:41], v[94:97], v[220:223], v[38:41]
	v_mfma_f32_16x16x32_bf16 v[28:31], v[86:89], v[228:231], v[28:31]
	v_mfma_f32_16x16x32_bf16 v[20:23], v[94:97], v[228:231], v[20:23]
	v_mfma_f32_16x16x32_bf16 v[8:11], v[86:89], v[236:239], v[8:11]
	v_mfma_f32_16x16x32_bf16 v[0:3], v[94:97], v[236:239], v[0:3]
	v_mfma_f32_16x16x32_bf16 v[62:65], v[90:93], v[166:169], v[62:65]
	v_mfma_f32_16x16x32_bf16 v[58:61], v[102:105], v[166:169], v[58:61]
	v_mfma_f32_16x16x32_bf16 v[46:49], v[90:93], v[224:227], v[46:49]
	v_mfma_f32_16x16x32_bf16 v[38:41], v[102:105], v[224:227], v[38:41]
	v_mfma_f32_16x16x32_bf16 v[28:31], v[90:93], v[232:235], v[28:31]
	v_mfma_f32_16x16x32_bf16 v[20:23], v[102:105], v[232:235], v[20:23]
	v_mfma_f32_16x16x32_bf16 v[8:11], v[90:93], v[240:243], v[8:11]
	v_mfma_f32_16x16x32_bf16 v[0:3], v[102:105], v[240:243], v[0:3]
	s_barrier
	s_setprio 0
	s_add_i32 s82, s82, 2
	s_add_u32 s56, s56, 0x100
	s_addc_u32 s57, s57, 0
	s_add_u32 s47, s47, 0x100
	s_addc_u32 s77, s77, 0
	s_cmp_gt_u32 s82, 29
	s_cbranch_scc0 .LBB0_479
	s_and_b64 vcc, exec, s[34:35]
	s_cbranch_vccz .LBB0_482
	s_barrier

; #define PG8_STAGE(bufoff, gbase, voff) do { _Pragma("unroll") for (int _i = 0; _i < 2; ++_i) \
;         __builtin_amdgcn_global_load_lds((const unsigned*)((const char*)(gbase) + (voff)[_i]), (PG8_LAS unsigned*)(lds + (bufoff) + ldsw + _i * 8192), 16, 0, 0); } while (0)
; #define PG8_LDA(dst, b, h) do { _Pragma("unroll") for (int m = 0; m < 4; ++m) _Pragma("unroll") for (int k = 0; k < 2; ++k) dst[m][k] = *(const PG8_LAS bf16x8*)(lds + PG8_SA(b, h) + aoff + m * 2048 + k * 1024); } while (0)
; #define PG8_LDB(dst, b, h) do { _Pragma("unroll") for (int n = 0; n < 2; ++n) _Pragma("unroll") for (int k = 0; k < 2; ++k) dst[n][k] = *(const PG8_LAS bf16x8*)(lds + PG8_SB(b, h) + boff + n * 2048 + k * 1024); } while (0)
; #define PG8_MMA(ai, bj, At, Bt) do { __builtin_amdgcn_s_setprio(1); _Pragma("unroll") for (int m = 0; m < 4; ++m) _Pragma("unroll") for (int n = 0; n < 2; ++n) _Pragma("unroll") for (int k = 0; k < 2; ++k) \
;         acc[ai][bj][m][n] = __builtin_amdgcn_mfma_f32_16x16x32_bf16(Bt[n][k], At[m][k], acc[ai][bj][m][n], 0, 0, 0); __builtin_amdgcn_s_setprio(0); } while (0)
; #define PG8_WAIT_V(n) asm volatile("s_waitcnt vmcnt(" #n ")" ::: "memory")
; #define PG8_WAIT_L(n) asm volatile("s_waitcnt lgkmcnt(" #n ")" ::: "memory")
; template <class Epi, class Sched, bool ALIGN_EPI = false, bool SP2 = false>
; __device__ __forceinline__ void gemm_phase(PG8_LAS unsigned char* lds, const Gemm g, const Sched& S, const Epi& E, int tid_in) {
;     ...
;             const bool last = (t == nt - 2);
;             const char* a1 = cA + (size_t)(t + 1) * kstep;
;             const char* a2 = last ? nA : cA + (size_t)(t + 2) * kstep; const char* b2 = last ? nB : cB + (size_t)(t + 2) * kstep;
;             const char* a3 = a2 + kstep; const char* b3 = b2 + kstep;
;             if (last && has_next) S.a_ready(nxt);
;             if constexpr (SP2) {
;             PG8_LDB(B0, 0, 0); PG8_LDB(B1, 0, 1); PG8_SCHED; PG8_LDA(At, 0, 0); PG8_STAGE(PG8_SA(1, 1), a1 + hstep, voffA);
;             PG8_WAIT_V(8); PG8_WAIT_L(0); PG8_BAR; PG8_MMA(0, 0, At, B0); PG8_MMA(0, 1, At, B1); PG8_BAR; PG8_SCHED;
;             PG8_LDA(At, 0, 1); PG8_STAGE(PG8_SB(0, 0), b2, voffB); PG8_STAGE(PG8_SB(0, 1), b2 + hstep, voffB); PG8_STAGE(PG8_SA(0, 0), a2, voffA);
;             PG8_WAIT_V(8); PG8_WAIT_L(0); PG8_BAR; PG8_MMA(1, 0, At, B0); PG8_MMA(1, 1, At, B1); PG8_BAR; PG8_SCHED;
.LBB0_625:
	s_add_u32 s26, s24, 0x100
	s_addc_u32 s27, s25, 0
	s_add_i32 s58, 0, 0x10000
	s_cmpk_eq_i32 s57, 0x54
	s_cselect_b32 s31, s7, s27
	s_cselect_b32 s30, s6, s26
	s_cselect_b32 s29, s23, s47
	s_cselect_b32 s28, s22, s45
	s_add_i32 s59, 0, 0x14000
	v_add_u32_e32 v152, s58, v141
	v_add_u32_e32 v168, s59, v141
	ds_read_b128 v[136:139], v152
	ds_read_b128 v[144:147], v152 offset:1024
	ds_read_b128 v[148:151], v152 offset:2048
	ds_read_b128 v[152:155], v152 offset:3072
	ds_read_b128 v[156:159], v168
	ds_read_b128 v[160:163], v168 offset:1024
	ds_read_b128 v[164:167], v168 offset:2048
	ds_read_b128 v[186:189], v168 offset:3072
	v_lshl_add_u64 v[168:169], s[24:25], 0, v[132:133]
	s_add_i32 m0, s38, 0xc000
	ds_read_b128 v[190:193], v143
	ds_read_b128 v[194:197], v143 offset:1024
	ds_read_b128 v[212:215], v143 offset:2048
	ds_read_b128 v[220:223], v143 offset:3072
	ds_read_b128 v[224:227], v143 offset:4096
	ds_read_b128 v[228:231], v143 offset:5120
	ds_read_b128 v[232:235], v143 offset:6144
	ds_read_b128 v[236:239], v143 offset:7168
	global_load_lds_dwordx4 v[168:169], off
	v_lshl_add_u64 v[168:169], s[24:25], 0, v[134:135]
	s_add_i32 m0, s38, 0xe000
	s_nop 0
	global_load_lds_dwordx4 v[168:169], off
	s_waitcnt vmcnt(8)
	s_waitcnt lgkmcnt(0)
	s_setprio 1
	s_barrier
	v_mfma_f32_16x16x32_bf16 v[126:129], v[136:139], v[190:193], v[126:129]
	v_mfma_f32_16x16x32_bf16 v[122:125], v[148:151], v[190:193], v[122:125]
	v_mfma_f32_16x16x32_bf16 v[114:117], v[136:139], v[212:215], v[114:117]
	v_mfma_f32_16x16x32_bf16 v[110:113], v[148:151], v[212:215], v[110:113]
	v_mfma_f32_16x16x32_bf16 v[98:101], v[136:139], v[224:227], v[98:101]
	v_mfma_f32_16x16x32_bf16 v[94:97], v[148:151], v[224:227], v[94:97]
	v_mfma_f32_16x16x32_bf16 v[82:85], v[136:139], v[232:235], v[82:85]
	v_mfma_f32_16x16x32_bf16 v[78:81], v[148:151], v[232:235], v[78:81]
	v_mfma_f32_16x16x32_bf16 v[126:129], v[144:147], v[194:197], v[126:129]
	v_mfma_f32_16x16x32_bf16 v[122:125], v[152:155], v[194:197], v[122:125]
	v_mfma_f32_16x16x32_bf16 v[114:117], v[144:147], v[220:223], v[114:117]
	v_mfma_f32_16x16x32_bf16 v[110:113], v[152:155], v[220:223], v[110:113]
	v_mfma_f32_16x16x32_bf16 v[98:101], v[144:147], v[228:231], v[98:101]
	v_mfma_f32_16x16x32_bf16 v[94:97], v[152:155], v[228:231], v[94:97]
	v_mfma_f32_16x16x32_bf16 v[82:85], v[144:147], v[236:239], v[82:85]
	v_mfma_f32_16x16x32_bf16 v[78:81], v[152:155], v[236:239], v[78:81]
	s_setprio 0
	s_setprio 1
	v_mfma_f32_16x16x32_bf16 v[118:121], v[156:159], v[190:193], v[118:121]
	v_mfma_f32_16x16x32_bf16 v[106:109], v[164:167], v[190:193], v[106:109]
	v_mfma_f32_16x16x32_bf16 v[102:105], v[156:159], v[212:215], v[102:105]
	v_mfma_f32_16x16x32_bf16 v[90:93], v[164:167], v[212:215], v[90:93]
	v_mfma_f32_16x16x32_bf16 v[86:89], v[156:159], v[224:227], v[86:89]
	v_mfma_f32_16x16x32_bf16 v[74:77], v[164:167], v[224:227], v[74:77]
	v_mfma_f32_16x16x32_bf16 v[70:73], v[156:159], v[232:235], v[70:73]
	v_mfma_f32_16x16x32_bf16 v[66:69], v[164:167], v[232:235], v[66:69]
	v_mfma_f32_16x16x32_bf16 v[118:121], v[160:163], v[194:197], v[118:121]
	v_mfma_f32_16x16x32_bf16 v[106:109], v[186:189], v[194:197], v[106:109]
	v_mfma_f32_16x16x32_bf16 v[102:105], v[160:163], v[220:223], v[102:105]
	v_mfma_f32_16x16x32_bf16 v[90:93], v[186:189], v[220:223], v[90:93]
	v_mfma_f32_16x16x32_bf16 v[86:89], v[160:163], v[228:231], v[86:89]
	v_mfma_f32_16x16x32_bf16 v[74:77], v[186:189], v[228:231], v[74:77]
	v_mfma_f32_16x16x32_bf16 v[70:73], v[160:163], v[236:239], v[70:73]
	v_mfma_f32_16x16x32_bf16 v[66:69], v[186:189], v[236:239], v[66:69]
	s_barrier
	s_setprio 0
	s_add_i32 s24, s58, s35
	v_lshl_add_u64 v[168:169], s[28:29], 0, v[32:33]
	s_mov_b32 m0, s24
	ds_read_b128 v[190:193], v143 offset:16384
	ds_read_b128 v[194:197], v143 offset:17408
	ds_read_b128 v[212:215], v143 offset:18432
	ds_read_b128 v[220:223], v143 offset:19456
	ds_read_b128 v[224:227], v143 offset:20480
	ds_read_b128 v[228:231], v143 offset:21504
	ds_read_b128 v[232:235], v143 offset:22528
	ds_read_b128 v[236:239], v143 offset:23552
	global_load_lds_dwordx4 v[168:169], off
	s_add_i32 m0, s24, 0x2000
	s_add_u32 s24, s28, 0x160000
	v_lshl_add_u64 v[216:217], s[28:29], 0, v[130:131]
	s_addc_u32 s25, s29, 0
	s_add_i32 s58, s59, s35
	global_load_lds_dwordx4 v[216:217], off
	v_lshl_add_u64 v[240:241], s[24:25], 0, v[32:33]
	s_mov_b32 m0, s58
	v_lshl_add_u64 v[242:243], s[30:31], 0, v[130:131]
	global_load_lds_dwordx4 v[240:241], off
	v_lshl_add_u64 v[240:241], s[24:25], 0, v[130:131]
	s_add_i32 m0, s58, 0x2000
	s_nop 0
	global_load_lds_dwordx4 v[240:241], off
	v_lshl_add_u64 v[240:241], s[30:31], 0, v[32:33]
	s_mov_b32 m0, s38
	s_nop 0
	global_load_lds_dwordx4 v[240:241], off
	s_mov_b32 m0, s39
	s_nop 0
	global_load_lds_dwordx4 v[242:243], off
	s_waitcnt vmcnt(8)
	s_waitcnt lgkmcnt(0)
	s_setprio 1
	s_barrier
; #define PG8_STAGE(bufoff, gbase, voff) do { _Pragma("unroll") for (int _i = 0; _i < 2; ++_i) \
;         __builtin_amdgcn_global_load_lds((const unsigned*)((const char*)(gbase) + (voff)[_i]), (PG8_LAS unsigned*)(lds + (bufoff) + ldsw + _i * 8192), 16, 0, 0); } while (0)
; #define PG8_LDA(dst, b, h) do { _Pragma("unroll") for (int m = 0; m < 4; ++m) _Pragma("unroll") for (int k = 0; k < 2; ++k) dst[m][k] = *(const PG8_LAS bf16x8*)(lds + PG8_SA(b, h) + aoff + m * 2048 + k * 1024); } while (0)
; #define PG8_LDB(dst, b, h) do { _Pragma("unroll") for (int n = 0; n < 2; ++n) _Pragma("unroll") for (int k = 0; k < 2; ++k) dst[n][k] = *(const PG8_LAS bf16x8*)(lds + PG8_SB(b, h) + boff + n * 2048 + k * 1024); } while (0)
; #define PG8_MMA(ai, bj, At, Bt) do { __builtin_amdgcn_s_setprio(1); _Pragma("unroll") for (int m = 0; m < 4; ++m) _Pragma("unroll") for (int n = 0; n < 2; ++n) _Pragma("unroll") for (int k = 0; k < 2; ++k) \
;         acc[ai][bj][m][n] = __builtin_amdgcn_mfma_f32_16x16x32_bf16(Bt[n][k], At[m][k], acc[ai][bj][m][n], 0, 0, 0); __builtin_amdgcn_s_setprio(0); } while (0)
; #define PG8_WAIT_V(n) asm volatile("s_waitcnt vmcnt(" #n ")" ::: "memory")
; #define PG8_WAIT_L(n) asm volatile("s_waitcnt lgkmcnt(" #n ")" ::: "memory")
; #define PG8_BAR __builtin_amdgcn_s_barrier()
; #define PG8_SCHED __builtin_amdgcn_sched_barrier(0)
; template <class Epi, class Sched, bool ALIGN_EPI = false, bool SP2 = false>
; __device__ __forceinline__ void gemm_phase(PG8_LAS unsigned char* lds, const Gemm g, const Sched& S, const Epi& E, int tid_in) {
;     ...
;             PG8_WAIT_V(8); PG8_WAIT_L(0); PG8_BAR; PG8_MMA(1, 0, At, B0); PG8_MMA(1, 1, At, B1); PG8_BAR; PG8_SCHED;
;             PG8_LDB(B0, 1, 0); PG8_LDB(B1, 1, 1); PG8_SCHED; PG8_LDA(At, 1, 0); PG8_STAGE(PG8_SA(0, 1), a2 + hstep, voffA);
;             PG8_WAIT_V(8); PG8_WAIT_L(0); PG8_BAR; PG8_MMA(0, 0, At, B0); PG8_MMA(0, 1, At, B1); PG8_BAR; PG8_SCHED;
	v_mfma_f32_16x16x32_bf16 v[62:65], v[136:139], v[190:193], v[62:65]
	v_mfma_f32_16x16x32_bf16 v[58:61], v[148:151], v[190:193], v[58:61]
	v_mfma_f32_16x16x32_bf16 v[50:53], v[136:139], v[212:215], v[50:53]
	v_mfma_f32_16x16x32_bf16 v[46:49], v[148:151], v[212:215], v[46:49]
	v_mfma_f32_16x16x32_bf16 v[34:37], v[136:139], v[224:227], v[34:37]
	v_mfma_f32_16x16x32_bf16 v[28:31], v[148:151], v[224:227], v[28:31]
	v_mfma_f32_16x16x32_bf16 v[16:19], v[136:139], v[232:235], v[16:19]
	v_mfma_f32_16x16x32_bf16 v[12:15], v[148:151], v[232:235], v[12:15]
	v_mfma_f32_16x16x32_bf16 v[62:65], v[144:147], v[194:197], v[62:65]
	v_mfma_f32_16x16x32_bf16 v[58:61], v[152:155], v[194:197], v[58:61]
	v_mfma_f32_16x16x32_bf16 v[50:53], v[144:147], v[220:223], v[50:53]
	v_mfma_f32_16x16x32_bf16 v[46:49], v[152:155], v[220:223], v[46:49]
	v_mfma_f32_16x16x32_bf16 v[34:37], v[144:147], v[228:231], v[34:37]
	v_mfma_f32_16x16x32_bf16 v[28:31], v[152:155], v[228:231], v[28:31]
	v_mfma_f32_16x16x32_bf16 v[16:19], v[144:147], v[236:239], v[16:19]
	v_mfma_f32_16x16x32_bf16 v[12:15], v[152:155], v[236:239], v[12:15]
	s_setprio 0
	s_setprio 1
	v_mfma_f32_16x16x32_bf16 v[54:57], v[156:159], v[190:193], v[54:57]
	v_mfma_f32_16x16x32_bf16 v[42:45], v[164:167], v[190:193], v[42:45]
	v_mfma_f32_16x16x32_bf16 v[38:41], v[156:159], v[212:215], v[38:41]
	v_mfma_f32_16x16x32_bf16 v[24:27], v[164:167], v[212:215], v[24:27]
	v_mfma_f32_16x16x32_bf16 v[20:23], v[156:159], v[224:227], v[20:23]
	v_mfma_f32_16x16x32_bf16 v[8:11], v[164:167], v[224:227], v[8:11]
	v_mfma_f32_16x16x32_bf16 v[4:7], v[156:159], v[232:235], v[4:7]
	v_mfma_f32_16x16x32_bf16 v[0:3], v[164:167], v[232:235], v[0:3]
	v_mfma_f32_16x16x32_bf16 v[54:57], v[160:163], v[194:197], v[54:57]
	v_mfma_f32_16x16x32_bf16 v[42:45], v[186:189], v[194:197], v[42:45]
	v_mfma_f32_16x16x32_bf16 v[38:41], v[160:163], v[220:223], v[38:41]
	v_mfma_f32_16x16x32_bf16 v[24:27], v[186:189], v[220:223], v[24:27]
	v_mfma_f32_16x16x32_bf16 v[20:23], v[160:163], v[228:231], v[20:23]
	v_mfma_f32_16x16x32_bf16 v[8:11], v[186:189], v[228:231], v[8:11]
	v_mfma_f32_16x16x32_bf16 v[4:7], v[160:163], v[236:239], v[4:7]
	v_mfma_f32_16x16x32_bf16 v[0:3], v[186:189], v[236:239], v[0:3]
	s_barrier
	s_setprio 0
	s_add_i32 s58, 0, 0x18000
	s_add_i32 s59, 0, 0x1c000
	v_add_u32_e32 v152, s58, v141
	v_add_u32_e32 v170, s59, v141
	ds_read_b128 v[136:139], v152
	ds_read_b128 v[144:147], v152 offset:1024
	ds_read_b128 v[148:151], v152 offset:2048
	ds_read_b128 v[152:155], v152 offset:3072
	ds_read_b128 v[156:159], v170
	ds_read_b128 v[160:163], v170 offset:1024
	ds_read_b128 v[164:167], v170 offset:2048
	ds_read_b128 v[186:189], v170 offset:3072
	s_add_u32 s24, s30, 0x160000
	s_addc_u32 s25, s31, 0
	s_mov_b32 m0, s42
	v_lshl_add_u64 v[244:245], s[24:25], 0, v[32:33]
	ds_read_b128 v[190:193], v143 offset:32768
	ds_read_b128 v[194:197], v143 offset:33792
	ds_read_b128 v[212:215], v143 offset:34816
	ds_read_b128 v[220:223], v143 offset:35840
	ds_read_b128 v[224:227], v143 offset:36864
	ds_read_b128 v[228:231], v143 offset:37888
	ds_read_b128 v[232:235], v143 offset:38912
	ds_read_b128 v[236:239], v143 offset:39936
	global_load_lds_dwordx4 v[244:245], off
	v_lshl_add_u64 v[244:245], s[24:25], 0, v[130:131]
	s_mov_b32 m0, s43
	s_nop 0
	global_load_lds_dwordx4 v[244:245], off
	s_waitcnt vmcnt(8)
	s_waitcnt lgkmcnt(0)
	s_setprio 1
	s_barrier
	v_mfma_f32_16x16x32_bf16 v[126:129], v[136:139], v[190:193], v[126:129]
	v_mfma_f32_16x16x32_bf16 v[122:125], v[148:151], v[190:193], v[122:125]
	v_mfma_f32_16x16x32_bf16 v[114:117], v[136:139], v[212:215], v[114:117]
	v_mfma_f32_16x16x32_bf16 v[110:113], v[148:151], v[212:215], v[110:113]
	v_mfma_f32_16x16x32_bf16 v[98:101], v[136:139], v[224:227], v[98:101]
	v_mfma_f32_16x16x32_bf16 v[94:97], v[148:151], v[224:227], v[94:97]
	v_mfma_f32_16x16x32_bf16 v[82:85], v[136:139], v[232:235], v[82:85]
	v_mfma_f32_16x16x32_bf16 v[78:81], v[148:151], v[232:235], v[78:81]
	v_mfma_f32_16x16x32_bf16 v[126:129], v[144:147], v[194:197], v[126:129]
	v_mfma_f32_16x16x32_bf16 v[122:125], v[152:155], v[194:197], v[122:125]
	v_mfma_f32_16x16x32_bf16 v[114:117], v[144:147], v[220:223], v[114:117]
	v_mfma_f32_16x16x32_bf16 v[110:113], v[152:155], v[220:223], v[110:113]
	v_mfma_f32_16x16x32_bf16 v[98:101], v[144:147], v[228:231], v[98:101]
	v_mfma_f32_16x16x32_bf16 v[94:97], v[152:155], v[228:231], v[94:97]
	v_mfma_f32_16x16x32_bf16 v[82:85], v[144:147], v[236:239], v[82:85]
	v_mfma_f32_16x16x32_bf16 v[78:81], v[152:155], v[236:239], v[78:81]
	s_setprio 0
	s_setprio 1
	v_mfma_f32_16x16x32_bf16 v[118:121], v[156:159], v[190:193], v[118:121]
	v_mfma_f32_16x16x32_bf16 v[106:109], v[164:167], v[190:193], v[106:109]
	v_mfma_f32_16x16x32_bf16 v[102:105], v[156:159], v[212:215], v[102:105]
	v_mfma_f32_16x16x32_bf16 v[90:93], v[164:167], v[212:215], v[90:93]
	v_mfma_f32_16x16x32_bf16 v[86:89], v[156:159], v[224:227], v[86:89]
	v_mfma_f32_16x16x32_bf16 v[74:77], v[164:167], v[224:227], v[74:77]
	v_mfma_f32_16x16x32_bf16 v[70:73], v[156:159], v[232:235], v[70:73]
	v_mfma_f32_16x16x32_bf16 v[66:69], v[164:167], v[232:235], v[66:69]
	v_mfma_f32_16x16x32_bf16 v[118:121], v[160:163], v[194:197], v[118:121]
	v_mfma_f32_16x16x32_bf16 v[106:109], v[186:189], v[194:197], v[106:109]
	v_mfma_f32_16x16x32_bf16 v[102:105], v[160:163], v[220:223], v[102:105]
	v_mfma_f32_16x16x32_bf16 v[90:93], v[186:189], v[220:223], v[90:93]
	v_mfma_f32_16x16x32_bf16 v[86:89], v[160:163], v[228:231], v[86:89]
	v_mfma_f32_16x16x32_bf16 v[74:77], v[186:189], v[228:231], v[74:77]
	v_mfma_f32_16x16x32_bf16 v[70:73], v[160:163], v[236:239], v[70:73]
	v_mfma_f32_16x16x32_bf16 v[66:69], v[186:189], v[236:239], v[66:69]
	s_barrier
; #define PG8_STAGE(bufoff, gbase, voff) do { _Pragma("unroll") for (int _i = 0; _i < 2; ++_i) \
;         __builtin_amdgcn_global_load_lds((const unsigned*)((const char*)(gbase) + (voff)[_i]), (PG8_LAS unsigned*)(lds + (bufoff) + ldsw + _i * 8192), 16, 0, 0); } while (0)
; #define PG8_LDA(dst, b, h) do { _Pragma("unroll") for (int m = 0; m < 4; ++m) _Pragma("unroll") for (int k = 0; k < 2; ++k) dst[m][k] = *(const PG8_LAS bf16x8*)(lds + PG8_SA(b, h) + aoff + m * 2048 + k * 1024); } while (0)
; #define PG8_MMA(ai, bj, At, Bt) do { __builtin_amdgcn_s_setprio(1); _Pragma("unroll") for (int m = 0; m < 4; ++m) _Pragma("unroll") for (int n = 0; n < 2; ++n) _Pragma("unroll") for (int k = 0; k < 2; ++k) \
;         acc[ai][bj][m][n] = __builtin_amdgcn_mfma_f32_16x16x32_bf16(Bt[n][k], At[m][k], acc[ai][bj][m][n], 0, 0, 0); __builtin_amdgcn_s_setprio(0); } while (0)
; #define PG8_WAIT_V(n) asm volatile("s_waitcnt vmcnt(" #n ")" ::: "memory")
; #define PG8_WAIT_L(n) asm volatile("s_waitcnt lgkmcnt(" #n ")" ::: "memory")
; #define PG8_BAR __builtin_amdgcn_s_barrier()
; #define PG8_SCHED __builtin_amdgcn_sched_barrier(0)
; template <class Epi, class Sched, bool ALIGN_EPI = false, bool SP2 = false>
; __device__ __forceinline__ void gemm_phase(PG8_LAS unsigned char* lds, const Gemm g, const Sched& S, const Epi& E, int tid_in) {
;     ...
;         for (int t = 0; t < nt; t += 2) {
;     ...
;             PG8_LDA(At, 1, 1); PG8_STAGE(PG8_SB(1, 0), b3, voffB); PG8_STAGE(PG8_SB(1, 1), b3 + hstep, voffB); PG8_STAGE(PG8_SA(1, 0), a3, voffA);
;             PG8_WAIT_V(8); PG8_WAIT_L(0); PG8_BAR; PG8_MMA(1, 0, At, B0); PG8_MMA(1, 1, At, B1); PG8_BAR; PG8_SCHED;
	s_setprio 0
	s_add_i32 s24, s58, s35
	v_lshl_add_u64 v[168:169], v[168:169], 0, s[74:75]
	s_mov_b32 m0, s24
	ds_read_b128 v[190:193], v143 offset:49152
	ds_read_b128 v[194:197], v143 offset:50176
	ds_read_b128 v[212:215], v143 offset:51200
	ds_read_b128 v[220:223], v143 offset:52224
	ds_read_b128 v[224:227], v143 offset:53248
	ds_read_b128 v[228:231], v143 offset:54272
	ds_read_b128 v[232:235], v143 offset:55296
	ds_read_b128 v[236:239], v143 offset:56320
	global_load_lds_dwordx4 v[168:169], off
	s_add_i32 m0, s24, 0x2000
	s_add_u32 s24, s28, 0x160080
	v_lshl_add_u64 v[168:169], v[216:217], 0, s[74:75]
	s_addc_u32 s25, s29, 0
	s_add_i32 s28, s59, s35
	global_load_lds_dwordx4 v[168:169], off
	v_lshl_add_u64 v[168:169], s[24:25], 0, v[32:33]
	s_mov_b32 m0, s28
	s_nop 0
	global_load_lds_dwordx4 v[168:169], off
	v_lshl_add_u64 v[168:169], s[24:25], 0, v[130:131]
	s_add_i32 m0, s28, 0x2000
	s_nop 0
	global_load_lds_dwordx4 v[168:169], off
	v_lshl_add_u64 v[168:169], v[240:241], 0, s[74:75]
	s_mov_b32 m0, s48
	s_nop 0
	global_load_lds_dwordx4 v[168:169], off
	v_lshl_add_u64 v[168:169], v[242:243], 0, s[74:75]
	s_mov_b32 m0, s49
	s_nop 0
	global_load_lds_dwordx4 v[168:169], off
	s_waitcnt vmcnt(8)
	s_waitcnt lgkmcnt(0)
	s_setprio 1
	s_barrier
	v_mfma_f32_16x16x32_bf16 v[62:65], v[136:139], v[190:193], v[62:65]
	v_mfma_f32_16x16x32_bf16 v[58:61], v[148:151], v[190:193], v[58:61]
	v_mfma_f32_16x16x32_bf16 v[50:53], v[136:139], v[212:215], v[50:53]
	v_mfma_f32_16x16x32_bf16 v[46:49], v[148:151], v[212:215], v[46:49]
	v_mfma_f32_16x16x32_bf16 v[34:37], v[136:139], v[224:227], v[34:37]
	v_mfma_f32_16x16x32_bf16 v[28:31], v[148:151], v[224:227], v[28:31]
	v_mfma_f32_16x16x32_bf16 v[16:19], v[136:139], v[232:235], v[16:19]
	v_mfma_f32_16x16x32_bf16 v[12:15], v[148:151], v[232:235], v[12:15]
	v_mfma_f32_16x16x32_bf16 v[62:65], v[144:147], v[194:197], v[62:65]
	v_mfma_f32_16x16x32_bf16 v[58:61], v[152:155], v[194:197], v[58:61]
	v_mfma_f32_16x16x32_bf16 v[50:53], v[144:147], v[220:223], v[50:53]
	v_mfma_f32_16x16x32_bf16 v[46:49], v[152:155], v[220:223], v[46:49]
	v_mfma_f32_16x16x32_bf16 v[34:37], v[144:147], v[228:231], v[34:37]
	v_mfma_f32_16x16x32_bf16 v[28:31], v[152:155], v[228:231], v[28:31]
	v_mfma_f32_16x16x32_bf16 v[16:19], v[144:147], v[236:239], v[16:19]
	v_mfma_f32_16x16x32_bf16 v[12:15], v[152:155], v[236:239], v[12:15]
	s_setprio 0
	s_setprio 1
	v_mfma_f32_16x16x32_bf16 v[54:57], v[156:159], v[190:193], v[54:57]
	v_mfma_f32_16x16x32_bf16 v[42:45], v[164:167], v[190:193], v[42:45]
	v_mfma_f32_16x16x32_bf16 v[38:41], v[156:159], v[212:215], v[38:41]
	v_mfma_f32_16x16x32_bf16 v[24:27], v[164:167], v[212:215], v[24:27]
	v_mfma_f32_16x16x32_bf16 v[20:23], v[156:159], v[224:227], v[20:23]
	v_mfma_f32_16x16x32_bf16 v[8:11], v[164:167], v[224:227], v[8:11]
	v_mfma_f32_16x16x32_bf16 v[4:7], v[156:159], v[232:235], v[4:7]
	v_mfma_f32_16x16x32_bf16 v[0:3], v[164:167], v[232:235], v[0:3]
	v_mfma_f32_16x16x32_bf16 v[54:57], v[160:163], v[194:197], v[54:57]
	v_mfma_f32_16x16x32_bf16 v[42:45], v[186:189], v[194:197], v[42:45]
	v_mfma_f32_16x16x32_bf16 v[38:41], v[160:163], v[220:223], v[38:41]
	v_mfma_f32_16x16x32_bf16 v[24:27], v[186:189], v[220:223], v[24:27]
	v_mfma_f32_16x16x32_bf16 v[20:23], v[160:163], v[228:231], v[20:23]
	v_mfma_f32_16x16x32_bf16 v[8:11], v[186:189], v[228:231], v[8:11]
	v_mfma_f32_16x16x32_bf16 v[4:7], v[160:163], v[236:239], v[4:7]
	v_mfma_f32_16x16x32_bf16 v[0:3], v[186:189], v[236:239], v[0:3]
	s_barrier
	s_setprio 0
	s_add_i32 s57, s57, 2
	s_add_u32 s45, s45, 0x100
	s_addc_u32 s47, s47, 0
	s_cmpk_gt_u32 s57, 0x55
	s_mov_b64 s[24:25], s[26:27]
	s_cbranch_scc0 .LBB0_625
	s_and_b64 vcc, exec, s[20:21]
	s_cbranch_vccz .LBB0_628
	s_barrier
